# p4new + LayerNorm row statistics: xor-16/xor-32 reductions via v_permlane16/32_swap instead of ds_bpermute round trips (64 sites)
# baseline (speedup 1.0000x reference)
; #define PG8_LAS __attribute__((address_space(3)))
;     __device__ __forceinline__ void fused(f32x4 (&acc)[2][2][4][2], const Unit& u, int wr, int wc, int fr, int fq, PG8_LAS unsigned char* lds, int wid, int lane) const {
;         typedef float f32x2v __attribute__((ext_vector_type(2)));
;         const PG8_LAS f32x2v* S = (const PG8_LAS f32x2v*)(lds + 8192);
;         const int col0 = u.pn * BM + wc * 32 + 8 * fq;
; #pragma unroll
;         for (int ai = 0; ai < 2; ++ai) {
;             f32x4 bs[4][2][2];
; #pragma unroll
;             for (int m = 0; m < 4; ++m) { const size_t off = (size_t)(u.pm * BM + ai * HALF + wr * 64 + m * 16 + fr) * ldc + col0;
; #pragma unroll
;                 for (int bj = 0; bj < 2; ++bj) { if (baseb) unpack8(*(const u32x4*)(baseb + off + bj * HALF), bs[m][bj][0], bs[m][bj][1]);
;                     else { bs[m][bj][0] = *(const f32x4*)(base + off + bj * HALF); bs[m][bj][1] = *(const f32x4*)(base + off + bj * HALF + 4); } } }
;             asm volatile("" ::: "memory");
; #pragma unroll
;             for (int m = 0; m < 4; ++m) {
; #pragma unroll
;                 for (int bj = 0; bj < 2; ++bj)
; #pragma unroll
;                     for (int n = 0; n < 2; ++n) acc[ai][bj][m][n] += bs[m][bj][n] * ALPHA;
;                 asm volatile("" : "+v"(acc[ai][0][m][0]), "+v"(acc[ai][0][m][1]), "+v"(acc[ai][1][m][0]), "+v"(acc[ai][1][m][1])); }
;             asm volatile("" ::: "memory");
.LBB0_1093:
	s_lshl_b32 s7, s10, 8
	s_lshl_b32 s0, s11, 5
	s_lshl_b32 s1, s18, 8
	v_add_u32_e32 v164, s7, v170
	s_or_b32 s0, s1, s0
	v_or_b32_e32 v140, 16, v164
	v_or_b32_e32 v148, 32, v164
	v_and_or_b32 v138, v151, 24, s0
	v_ashrrev_i32_e32 v165, 31, v164
	v_ashrrev_i32_e32 v141, 31, v140
	v_ashrrev_i32_e32 v149, 31, v148
	v_ashrrev_i32_e32 v139, 31, v138
	v_lshlrev_b64 v[126:127], 11, v[164:165]
	v_lshlrev_b64 v[140:141], 11, v[140:141]
	v_lshlrev_b64 v[148:149], 11, v[148:149]
	v_lshl_add_u64 v[126:127], s[20:21], 0, v[126:127]
	v_lshlrev_b64 v[162:163], 1, v[138:139]
	v_lshl_add_u64 v[140:141], s[20:21], 0, v[140:141]
	v_lshl_add_u64 v[148:149], s[20:21], 0, v[148:149]
	v_lshl_add_u64 v[166:167], v[126:127], 0, v[162:163]
	v_lshl_add_u64 v[144:145], v[140:141], 0, v[162:163]
	v_lshl_add_u64 v[148:149], v[148:149], 0, v[162:163]
	s_barrier
	global_load_dwordx4 v[126:129], v[166:167], off
	global_load_dwordx4 v[130:133], v[166:167], off offset:256
	global_load_dwordx4 v[140:143], v[144:145], off
	s_nop 0
	global_load_dwordx4 v[144:147], v[144:145], off offset:256
	s_nop 0
	global_load_dwordx4 v[152:155], v[148:149], off
	global_load_dwordx4 v[156:159], v[148:149], off offset:256
	v_or_b32_e32 v148, 48, v164
	v_ashrrev_i32_e32 v149, 31, v148
	v_lshlrev_b64 v[148:149], 11, v[148:149]
	v_lshl_add_u64 v[148:149], s[20:21], 0, v[148:149]
	v_lshl_add_u64 v[148:149], v[148:149], 0, v[162:163]
	global_load_dwordx4 v[172:175], v[148:149], off
	global_load_dwordx4 v[176:179], v[148:149], off offset:256
	s_mov_b32 s6, 0x3f9837f0
	v_cmp_gt_u32_e32 vcc, 16, v234
	s_waitcnt vmcnt(0)
	v_lshlrev_b32_e32 v148, 16, v126
	v_and_b32_e32 v149, 0xffff0000, v126
	v_lshlrev_b32_e32 v126, 16, v127
	v_and_b32_e32 v127, 0xffff0000, v127
	v_lshlrev_b32_e32 v160, 16, v128
	v_and_b32_e32 v161, 0xffff0000, v128
	v_lshlrev_b32_e32 v182, 16, v131
	v_and_b32_e32 v183, 0xffff0000, v131
	v_lshlrev_b32_e32 v184, 16, v132
	v_and_b32_e32 v185, 0xffff0000, v132
	v_lshlrev_b32_e32 v188, 16, v140
	v_and_b32_e32 v189, 0xffff0000, v140
	v_lshlrev_b32_e32 v140, 16, v141
	v_and_b32_e32 v141, 0xffff0000, v141
	v_lshlrev_b32_e32 v194, 16, v146
	v_and_b32_e32 v195, 0xffff0000, v146
	v_lshlrev_b32_e32 v200, 16, v156
	v_and_b32_e32 v201, 0xffff0000, v156
	v_lshlrev_b32_e32 v202, 16, v158
	v_and_b32_e32 v203, 0xffff0000, v158
	v_lshlrev_b32_e32 v204, 16, v172
	v_and_b32_e32 v205, 0xffff0000, v172
	v_lshlrev_b32_e32 v168, 16, v129
	v_and_b32_e32 v169, 0xffff0000, v129
	v_lshlrev_b32_e32 v180, 16, v130
	v_and_b32_e32 v181, 0xffff0000, v130
	v_pk_fma_f32 v[128:129], v[126:127], s[6:7], v[124:125] op_sel_hi:[1,0,1]
	v_pk_fma_f32 v[130:131], v[160:161], s[6:7], v[118:119] op_sel_hi:[1,0,1]
	v_pk_fma_f32 v[124:125], v[182:183], s[6:7], v[108:109] op_sel_hi:[1,0,1]
	v_pk_fma_f32 v[118:119], v[184:185], s[6:7], v[94:95] op_sel_hi:[1,0,1]
	v_pk_fma_f32 v[108:109], v[140:141], s[6:7], v[116:117] op_sel_hi:[1,0,1]
	v_pk_fma_f32 v[94:95], v[194:195], s[6:7], v[82:83] op_sel_hi:[1,0,1]
	v_pk_fma_f32 v[82:83], v[200:201], s[6:7], v[78:79] op_sel_hi:[1,0,1]
	v_pk_fma_f32 v[78:79], v[202:203], s[6:7], v[74:75] op_sel_hi:[1,0,1]
	v_pk_fma_f32 v[74:75], v[204:205], s[6:7], v[110:111] op_sel_hi:[1,0,1]
	v_add_u32_e32 v110, 0x80, v164
	v_add_u32_e32 v140, 0x90, v164
	v_pk_fma_f32 v[126:127], v[148:149], s[6:7], v[122:123] op_sel_hi:[1,0,1]
	v_ashrrev_i32_e32 v111, 31, v110
	v_ashrrev_i32_e32 v141, 31, v140
	v_add_u32_e32 v148, 0xa0, v164
	v_lshlrev_b32_e32 v186, 16, v133
	v_and_b32_e32 v187, 0xffff0000, v133
	v_lshlrev_b32_e32 v190, 16, v142
	v_and_b32_e32 v191, 0xffff0000, v142
	v_lshlrev_b32_e32 v142, 16, v143
	v_and_b32_e32 v143, 0xffff0000, v143
	v_lshlrev_b32_e32 v192, 16, v144
	v_and_b32_e32 v193, 0xffff0000, v144
	v_lshlrev_b32_e32 v144, 16, v145
	v_and_b32_e32 v145, 0xffff0000, v145
	v_lshlrev_b32_e32 v146, 16, v147
	v_and_b32_e32 v147, 0xffff0000, v147
	v_lshlrev_b32_e32 v196, 16, v152
	v_and_b32_e32 v197, 0xffff0000, v152
	v_lshlrev_b32_e32 v152, 16, v153
	v_and_b32_e32 v153, 0xffff0000, v153
	v_lshlrev_b32_e32 v198, 16, v154
	v_and_b32_e32 v199, 0xffff0000, v154
	v_lshlrev_b32_e32 v154, 16, v155
	v_and_b32_e32 v155, 0xffff0000, v155
	v_lshlrev_b32_e32 v156, 16, v157
	v_and_b32_e32 v157, 0xffff0000, v157
	v_lshlrev_b32_e32 v158, 16, v159
	v_and_b32_e32 v159, 0xffff0000, v159
	v_lshlrev_b32_e32 v172, 16, v173
	v_and_b32_e32 v173, 0xffff0000, v173
	v_lshlrev_b32_e32 v206, 16, v174
	v_and_b32_e32 v207, 0xffff0000, v174
	v_lshlrev_b32_e32 v174, 16, v175
	v_and_b32_e32 v175, 0xffff0000, v175
	v_lshlrev_b32_e32 v208, 16, v178
	v_and_b32_e32 v209, 0xffff0000, v178
	v_lshlrev_b32_e32 v178, 16, v179
	v_and_b32_e32 v179, 0xffff0000, v179
	v_lshlrev_b32_e32 v210, 16, v176
	v_and_b32_e32 v211, 0xffff0000, v176
	v_lshlrev_b32_e32 v176, 16, v177
	v_and_b32_e32 v177, 0xffff0000, v177
	v_lshlrev_b64 v[110:111], 11, v[110:111]
	v_lshlrev_b64 v[140:141], 11, v[140:141]
	v_ashrrev_i32_e32 v149, 31, v148
	v_pk_fma_f32 v[132:133], v[168:169], s[6:7], v[120:121] op_sel_hi:[1,0,1]
	v_pk_fma_f32 v[122:123], v[180:181], s[6:7], v[106:107] op_sel_hi:[1,0,1]
	v_pk_fma_f32 v[120:121], v[186:187], s[6:7], v[96:97] op_sel_hi:[1,0,1]
	v_pk_fma_f32 v[106:107], v[188:189], s[6:7], v[114:115] op_sel_hi:[1,0,1]
	v_pk_fma_f32 v[116:117], v[142:143], s[6:7], v[100:101] op_sel_hi:[1,0,1]
	v_pk_fma_f32 v[114:115], v[190:191], s[6:7], v[98:99] op_sel_hi:[1,0,1]
	v_pk_fma_f32 v[100:101], v[144:145], s[6:7], v[92:93] op_sel_hi:[1,0,1]
	v_pk_fma_f32 v[98:99], v[192:193], s[6:7], v[90:91] op_sel_hi:[1,0,1]
	v_pk_fma_f32 v[96:97], v[146:147], s[6:7], v[84:85] op_sel_hi:[1,0,1]
	v_pk_fma_f32 v[92:93], v[152:153], s[6:7], v[136:137] op_sel_hi:[1,0,1]
;     __device__ __forceinline__ bool run(const f32x4 (&v)[2][2][4][2], const Unit& u, int wr, int wc, int fr, int fq, PG8_LAS unsigned char* lds, int wid, int lane) const {
;     ...
;         for (int ai = 0; ai < 2; ++ai)
; #pragma unroll
;             for (int m = 0; m < 4; ++m) {
;                 float s = 0.f;
; #pragma unroll
;                 for (int bj = 0; bj < 2; ++bj)
; #pragma unroll
;                     for (int n = 0; n < 2; ++n) { const f32x4 x = v[ai][bj][m][n]; s += (x[0] + x[1]) + (x[2] + x[3]); }
;                 s += __shfl_xor(s, 16); s += __shfl_xor(s, 32);
;     __device__ __forceinline__ void fused(f32x4 (&acc)[2][2][4][2], const Unit& u, int wr, int wc, int fr, int fq, PG8_LAS unsigned char* lds, int wid, int lane) const {
;     ...
;         for (int ai = 0; ai < 2; ++ai) {
;             f32x4 bs[4][2][2];
; #pragma unroll
;             for (int m = 0; m < 4; ++m) { const size_t off = (size_t)(u.pm * BM + ai * HALF + wr * 64 + m * 16 + fr) * ldc + col0;
; #pragma unroll
;                 for (int bj = 0; bj < 2; ++bj) { if (baseb) unpack8(*(const u32x4*)(baseb + off + bj * HALF), bs[m][bj][0], bs[m][bj][1]);
;                     else { bs[m][bj][0] = *(const f32x4*)(base + off + bj * HALF); bs[m][bj][1] = *(const f32x4*)(base + off + bj * HALF + 4); } } }
;             asm volatile("" ::: "memory");
; #pragma unroll
;             for (int m = 0; m < 4; ++m) {
; #pragma unroll
;                 for (int bj = 0; bj < 2; ++bj)
; #pragma unroll
;                     for (int n = 0; n < 2; ++n) acc[ai][bj][m][n] += bs[m][bj][n] * ALPHA;
;                 asm volatile("" : "+v"(acc[ai][0][m][0]), "+v"(acc[ai][0][m][1]), "+v"(acc[ai][1][m][0]), "+v"(acc[ai][1][m][1])); }
;             asm volatile("" ::: "memory");
	v_pk_fma_f32 v[90:91], v[196:197], s[6:7], v[134:135] op_sel_hi:[1,0,1]
	v_pk_fma_f32 v[104:105], v[154:155], s[6:7], v[104:105] op_sel_hi:[1,0,1]
	v_pk_fma_f32 v[102:103], v[198:199], s[6:7], v[102:103] op_sel_hi:[1,0,1]
	v_pk_fma_f32 v[84:85], v[156:157], s[6:7], v[80:81] op_sel_hi:[1,0,1]
	v_pk_fma_f32 v[80:81], v[158:159], s[6:7], v[76:77] op_sel_hi:[1,0,1]
	v_pk_fma_f32 v[76:77], v[172:173], s[6:7], v[112:113] op_sel_hi:[1,0,1]
	v_pk_fma_f32 v[88:89], v[174:175], s[6:7], v[88:89] op_sel_hi:[1,0,1]
	v_pk_fma_f32 v[86:87], v[206:207], s[6:7], v[86:87] op_sel_hi:[1,0,1]
	v_pk_fma_f32 v[72:73], v[176:177], s[6:7], v[72:73] op_sel_hi:[1,0,1]
	v_pk_fma_f32 v[70:71], v[210:211], s[6:7], v[70:71] op_sel_hi:[1,0,1]
	v_pk_fma_f32 v[68:69], v[178:179], s[6:7], v[68:69] op_sel_hi:[1,0,1]
	v_pk_fma_f32 v[66:67], v[208:209], s[6:7], v[66:67] op_sel_hi:[1,0,1]
	v_lshl_add_u64 v[110:111], s[20:21], 0, v[110:111]
	v_lshl_add_u64 v[140:141], s[20:21], 0, v[140:141]
	v_lshlrev_b64 v[148:149], 11, v[148:149]
	v_lshl_add_u64 v[168:169], v[110:111], 0, v[162:163]
	v_lshl_add_u64 v[144:145], v[140:141], 0, v[162:163]
	v_lshl_add_u64 v[148:149], s[20:21], 0, v[148:149]
	global_load_dwordx4 v[110:113], v[168:169], off
	global_load_dwordx4 v[134:137], v[168:169], off offset:256
	global_load_dwordx4 v[140:143], v[144:145], off
	s_nop 0
	global_load_dwordx4 v[144:147], v[144:145], off offset:256
	v_lshl_add_u64 v[148:149], v[148:149], 0, v[162:163]
	global_load_dwordx4 v[156:159], v[148:149], off
	global_load_dwordx4 v[172:175], v[148:149], off offset:256
	v_add_u32_e32 v148, 0xb0, v164
	v_ashrrev_i32_e32 v149, 31, v148
	v_lshlrev_b64 v[148:149], 11, v[148:149]
	v_lshl_add_u64 v[148:149], s[20:21], 0, v[148:149]
	v_lshl_add_u64 v[148:149], v[148:149], 0, v[162:163]
	global_load_dwordx4 v[176:179], v[148:149], off
	global_load_dwordx4 v[180:183], v[148:149], off offset:256
	v_lshlrev_b32_e32 v154, 5, v150
	s_waitcnt vmcnt(7)
	v_lshlrev_b32_e32 v184, 16, v112
	v_and_b32_e32 v185, 0xffff0000, v112
	s_waitcnt vmcnt(6)
	v_lshlrev_b32_e32 v192, 16, v136
	v_and_b32_e32 v193, 0xffff0000, v136
	s_waitcnt vmcnt(4)
	v_lshlrev_b32_e32 v204, 16, v144
	v_and_b32_e32 v205, 0xffff0000, v144
	v_lshlrev_b32_e32 v208, 16, v146
	v_and_b32_e32 v209, 0xffff0000, v146
	s_waitcnt vmcnt(3)
	v_lshlrev_b32_e32 v212, 16, v156
	v_and_b32_e32 v213, 0xffff0000, v156
	v_lshlrev_b32_e32 v188, 16, v134
	v_and_b32_e32 v189, 0xffff0000, v134
	v_lshlrev_b32_e32 v190, 16, v135
	v_and_b32_e32 v191, 0xffff0000, v135
	v_pk_fma_f32 v[134:135], v[184:185], s[6:7], v[58:59] op_sel_hi:[1,0,1]
	v_pk_fma_f32 v[58:59], v[192:193], s[6:7], v[42:43] op_sel_hi:[1,0,1]
	v_pk_fma_f32 v[42:43], v[204:205], s[6:7], v[34:35] op_sel_hi:[1,0,1]
	v_pk_fma_f32 v[34:35], v[208:209], s[6:7], v[26:27] op_sel_hi:[1,0,1]
	v_pk_fma_f32 v[26:27], v[212:213], s[6:7], v[38:39] op_sel_hi:[1,0,1]
	v_mbcnt_lo_u32_b32 v38, -1, 0
	v_lshlrev_b32_e32 v186, 16, v113
	v_and_b32_e32 v187, 0xffff0000, v113
	v_lshlrev_b32_e32 v194, 16, v137
	v_and_b32_e32 v195, 0xffff0000, v137
	v_lshlrev_b32_e32 v206, 16, v145
	v_and_b32_e32 v207, 0xffff0000, v145
	v_lshlrev_b32_e32 v210, 16, v147
	v_and_b32_e32 v211, 0xffff0000, v147
	v_lshlrev_b32_e32 v156, 16, v157
	v_and_b32_e32 v157, 0xffff0000, v157
	v_mbcnt_hi_u32_b32 v39, -1, v38
	v_lshlrev_b32_e32 v160, 16, v110
	v_and_b32_e32 v161, 0xffff0000, v110
	v_lshlrev_b32_e32 v110, 16, v111
	v_and_b32_e32 v111, 0xffff0000, v111
	v_lshlrev_b32_e32 v196, 16, v140
	v_and_b32_e32 v197, 0xffff0000, v140
	v_pk_fma_f32 v[136:137], v[186:187], s[6:7], v[60:61] op_sel_hi:[1,0,1]
	v_pk_fma_f32 v[60:61], v[194:195], s[6:7], v[44:45] op_sel_hi:[1,0,1]
	v_pk_fma_f32 v[44:45], v[206:207], s[6:7], v[36:37] op_sel_hi:[1,0,1]
	v_pk_fma_f32 v[36:37], v[210:211], s[6:7], v[28:29] op_sel_hi:[1,0,1]
	v_pk_fma_f32 v[28:29], v[156:157], s[6:7], v[40:41] op_sel_hi:[1,0,1]
	v_and_b32_e32 v40, 64, v39
	v_lshlrev_b32_e32 v198, 16, v141
	v_and_b32_e32 v199, 0xffff0000, v141
	v_pk_fma_f32 v[112:113], v[110:111], s[6:7], v[64:65] op_sel_hi:[1,0,1]
	v_pk_fma_f32 v[110:111], v[160:161], s[6:7], v[62:63] op_sel_hi:[1,0,1]
	v_pk_fma_f32 v[62:63], v[188:189], s[6:7], v[50:51] op_sel_hi:[1,0,1]
	v_pk_fma_f32 v[50:51], v[196:197], s[6:7], v[54:55] op_sel_hi:[1,0,1]
	v_add_u32_e32 v155, 64, v40
	v_mov_b32_e32 v40, v127
	v_mov_b32_e32 v41, v128
	v_mov_b32_e32 v54, v126
	v_mov_b32_e32 v55, v129
	v_pk_fma_f32 v[64:65], v[190:191], s[6:7], v[52:53] op_sel_hi:[1,0,1]
	v_pk_fma_f32 v[52:53], v[198:199], s[6:7], v[56:57] op_sel_hi:[1,0,1]
	v_pk_add_f32 v[40:41], v[40:41], v[54:55]
	v_mov_b32_e32 v54, v131
	v_mov_b32_e32 v55, v132
	v_mov_b32_e32 v56, v130
	v_mov_b32_e32 v57, v133
	v_pk_add_f32 v[54:55], v[54:55], v[56:57]
	v_add_f32_e32 v40, v40, v41
	v_pk_add_f32 v[54:55], v[54:55], v[54:55] op_sel_hi:[0,1]
	v_xor_b32_e32 v38, 16, v39
	v_add_f32_e32 v41, 0, v40
	v_add_f32_e32 v57, v122, v123
	v_add_f32_e32 v157, v124, v125
	v_mov_b32_e32 v56, v118
	v_mov_b32_e32 v156, v119
	v_mov_b32_e32 v54, v120
	v_mov_b32_e32 v40, v121
	v_cmp_lt_i32_e64 s[0:1], v38, v155
	v_pk_add_f32 v[56:57], v[56:57], v[156:157]
	v_pk_add_f32 v[40:41], v[54:55], v[40:41]
	v_cndmask_b32_e64 v38, v39, v38, s[0:1]
	v_pk_add_f32 v[40:41], v[56:57], v[40:41]
	v_lshlrev_b32_e32 v38, 2, v38
	v_add_f32_e32 v40, v40, v41
	v_mov_b32_e32 v41, v40
	s_nop 1
	v_permlane16_swap_b32_e32 v41, v40
	v_xor_b32_e32 v54, 32, v39
	v_cmp_lt_i32_e64 s[0:1], v54, v155
	v_lshlrev_b32_e32 v200, 16, v142
	v_and_b32_e32 v201, 0xffff0000, v142
	v_cndmask_b32_e64 v39, v39, v54, s[0:1]
	v_lshlrev_b32_e32 v39, 2, v39
	s_waitcnt lgkmcnt(0)
;     __device__ __forceinline__ bool run(const f32x4 (&v)[2][2][4][2], const Unit& u, int wr, int wc, int fr, int fq, PG8_LAS unsigned char* lds, int wid, int lane) const {
;     ...
;                 s += __shfl_xor(s, 16); s += __shfl_xor(s, 32);
;                 const float mw = s * (1.0f / 64.0f); float q = 0.f;
; #pragma unroll
;                 for (int bj = 0; bj < 2; ++bj)
; #pragma unroll
;                     for (int n = 0; n < 2; ++n) { const f32x4 d = v[ai][bj][m][n] - mw; q += (d[0] * d[0] + d[1] * d[1]) + (d[2] * d[2] + d[3] * d[3]); }
;                 q += __shfl_xor(q, 16); q += __shfl_xor(q, 32);
;                 if (fq == 0) P[(ai * HALF + wr * 64 + m * 16 + fr) * 4 + wc] = (f32x2v){mw, q};
;             }
	v_add_f32_e32 v40, v40, v41
	v_mov_b32_e32 v41, v40
	s_nop 1
	v_permlane32_swap_b32_e32 v41, v40
	v_lshlrev_b32_e32 v202, 16, v143
	v_and_b32_e32 v203, 0xffff0000, v143
	v_lshlrev_b32_e32 v214, 16, v158
	v_and_b32_e32 v215, 0xffff0000, v158
	s_waitcnt lgkmcnt(0)
	v_add_f32_e32 v40, v40, v41
	v_fmamk_f32 v54, v40, 0xbc800000, v129
	v_fmamk_f32 v56, v40, 0xbc800000, v127
	v_fmamk_f32 v41, v40, 0xbc800000, v128
	v_fmamk_f32 v55, v40, 0xbc800000, v126
	v_mul_f32_e32 v56, v56, v56
	v_mul_f32_e32 v54, v54, v54
	v_fmac_f32_e32 v56, v55, v55
	v_fmac_f32_e32 v54, v41, v41
	v_fmamk_f32 v55, v40, 0xbc800000, v133
	v_fmamk_f32 v57, v40, 0xbc800000, v131
	v_add_f32_e32 v41, v56, v54
	v_fmamk_f32 v54, v40, 0xbc800000, v132
	v_fmamk_f32 v56, v40, 0xbc800000, v130
	v_mul_f32_e32 v57, v57, v57
	v_mul_f32_e32 v55, v55, v55
	v_fmac_f32_e32 v57, v56, v56
	v_fmac_f32_e32 v55, v54, v54
	v_add_f32_e32 v54, v57, v55
	v_fmamk_f32 v55, v40, 0xbc800000, v125
	v_fmamk_f32 v57, v40, 0xbc800000, v123
	v_add_f32_e32 v41, v41, v54
	v_fmamk_f32 v54, v40, 0xbc800000, v124
	v_fmamk_f32 v56, v40, 0xbc800000, v122
	v_mul_f32_e32 v57, v57, v57
	v_mul_f32_e32 v55, v55, v55
	v_fmac_f32_e32 v57, v56, v56
	v_fmac_f32_e32 v55, v54, v54
	v_add_f32_e32 v54, v57, v55
	v_fmamk_f32 v55, v40, 0xbc800000, v121
	v_fmamk_f32 v57, v40, 0xbc800000, v119
	v_add_f32_e32 v41, v54, v41
	v_fmamk_f32 v54, v40, 0xbc800000, v120
	v_fmamk_f32 v56, v40, 0xbc800000, v118
	v_mul_f32_e32 v57, v57, v57
	v_mul_f32_e32 v55, v55, v55
	v_fmac_f32_e32 v57, v56, v56
	v_fmac_f32_e32 v55, v54, v54
	v_add_f32_e32 v54, v57, v55
	v_add_f32_e32 v41, v54, v41
	v_mov_b32_e32 v54, v41
	s_nop 1
	v_permlane16_swap_b32_e32 v54, v41
	v_lshlrev_b32_e32 v158, 16, v159
	v_and_b32_e32 v159, 0xffff0000, v159
	s_waitcnt vmcnt(2)
	v_lshlrev_b32_e32 v216, 16, v172
	v_and_b32_e32 v217, 0xffff0000, v172
	s_waitcnt lgkmcnt(0)
	v_add_f32_e32 v41, v41, v54
	v_lshlrev_b32_e32 v172, 16, v173
	v_and_b32_e32 v173, 0xffff0000, v173
	v_lshlrev_b32_e32 v218, 16, v174
	v_and_b32_e32 v219, 0xffff0000, v174
	v_lshlrev_b32_e32 v174, 16, v175
	v_and_b32_e32 v175, 0xffff0000, v175
	s_waitcnt vmcnt(1)
	v_lshlrev_b32_e32 v146, 16, v176
	v_and_b32_e32 v147, 0xffff0000, v176
	v_lshlrev_b32_e32 v176, 16, v177
	v_and_b32_e32 v177, 0xffff0000, v177
	v_lshlrev_b32_e32 v148, 16, v178
	v_and_b32_e32 v149, 0xffff0000, v178
	v_lshlrev_b32_e32 v150, 16, v179
	v_and_b32_e32 v151, 0xffff0000, v179
	s_waitcnt vmcnt(0)
	v_lshlrev_b32_e32 v140, 16, v182
	v_and_b32_e32 v141, 0xffff0000, v182
	v_lshlrev_b32_e32 v142, 16, v183
	v_and_b32_e32 v143, 0xffff0000, v183
	v_lshlrev_b32_e32 v144, 16, v180
	v_and_b32_e32 v145, 0xffff0000, v180
	v_lshlrev_b32_e32 v152, 16, v181
	v_and_b32_e32 v153, 0xffff0000, v181
	v_mov_b32_e32 v54, v41
	s_nop 1
	v_permlane32_swap_b32_e32 v54, v41
	v_pk_fma_f32 v[48:49], v[202:203], s[6:7], v[48:49] op_sel_hi:[1,0,1]
	v_pk_fma_f32 v[46:47], v[200:201], s[6:7], v[46:47] op_sel_hi:[1,0,1]
	v_pk_fma_f32 v[32:33], v[158:159], s[6:7], v[32:33] op_sel_hi:[1,0,1]
	v_pk_fma_f32 v[30:31], v[214:215], s[6:7], v[30:31] op_sel_hi:[1,0,1]
	v_pk_fma_f32 v[24:25], v[172:173], s[6:7], v[24:25] op_sel_hi:[1,0,1]
	v_pk_fma_f32 v[22:23], v[216:217], s[6:7], v[22:23] op_sel_hi:[1,0,1]
	v_pk_fma_f32 v[20:21], v[174:175], s[6:7], v[20:21] op_sel_hi:[1,0,1]
	v_pk_fma_f32 v[18:19], v[218:219], s[6:7], v[18:19] op_sel_hi:[1,0,1]
	v_pk_fma_f32 v[16:17], v[176:177], s[6:7], v[16:17] op_sel_hi:[1,0,1]
	v_pk_fma_f32 v[14:15], v[146:147], s[6:7], v[14:15] op_sel_hi:[1,0,1]
	v_pk_fma_f32 v[12:13], v[150:151], s[6:7], v[12:13] op_sel_hi:[1,0,1]
	v_pk_fma_f32 v[10:11], v[148:149], s[6:7], v[10:11] op_sel_hi:[1,0,1]
	v_pk_fma_f32 v[8:9], v[152:153], s[6:7], v[8:9] op_sel_hi:[1,0,1]
	v_pk_fma_f32 v[6:7], v[144:145], s[6:7], v[6:7] op_sel_hi:[1,0,1]
	v_pk_fma_f32 v[4:5], v[142:143], s[6:7], v[4:5] op_sel_hi:[1,0,1]
	v_pk_fma_f32 v[2:3], v[140:141], s[6:7], v[2:3] op_sel_hi:[1,0,1]
	s_lshl_b32 s0, s11, 3
	s_add_i32 s6, s0, 0
	s_and_saveexec_b64 s[0:1], vcc
	s_cbranch_execz .LBB0_1095
	s_lshl_b32 s8, s35, 11
	s_add_i32 s8, s6, s8
	v_mul_f32_e32 v40, 0x3c800000, v40
	v_add_u32_e32 v55, s8, v154
	s_waitcnt lgkmcnt(0)
	v_add_f32_e32 v41, v41, v54
	ds_write_b64 v55, v[40:41]
.LBB0_1095:
	s_or_b64 exec, exec, s[0:1]
	v_mov_b32_e32 v40, v107
	v_mov_b32_e32 v41, v108
	s_waitcnt lgkmcnt(0)
	v_mov_b32_e32 v54, v106
	v_mov_b32_e32 v55, v109
	v_pk_add_f32 v[40:41], v[40:41], v[54:55]
	v_mov_b32_e32 v54, v115
	v_mov_b32_e32 v55, v116
	v_mov_b32_e32 v56, v114
	v_mov_b32_e32 v57, v117
	v_pk_add_f32 v[54:55], v[54:55], v[56:57]
	v_add_f32_e32 v40, v40, v41
	v_pk_add_f32 v[54:55], v[54:55], v[54:55] op_sel_hi:[0,1]
	v_add_f32_e32 v41, 0, v40
	v_add_f32_e32 v57, v98, v99
	v_add_f32_e32 v141, v100, v101
	v_mov_b32_e32 v56, v94
	v_mov_b32_e32 v140, v95
	v_mov_b32_e32 v54, v96
	v_mov_b32_e32 v40, v97
	v_pk_add_f32 v[56:57], v[56:57], v[140:141]
	v_pk_add_f32 v[40:41], v[54:55], v[40:41]
	s_nop 0
	v_pk_add_f32 v[40:41], v[56:57], v[40:41]
	s_nop 0
	v_add_f32_e32 v40, v40, v41
	v_mov_b32_e32 v41, v40
	s_nop 1
	v_permlane16_swap_b32_e32 v41, v40
	s_waitcnt lgkmcnt(0)
	v_add_f32_e32 v40, v40, v41
	v_mov_b32_e32 v41, v40
	s_nop 1
	v_permlane32_swap_b32_e32 v41, v40
	s_waitcnt lgkmcnt(0)
	v_add_f32_e32 v40, v40, v41
	v_fmamk_f32 v54, v40, 0xbc800000, v109
	v_fmamk_f32 v56, v40, 0xbc800000, v107
	v_fmamk_f32 v41, v40, 0xbc800000, v108
	v_fmamk_f32 v55, v40, 0xbc800000, v106
	v_mul_f32_e32 v56, v56, v56
	v_mul_f32_e32 v54, v54, v54
	v_fmac_f32_e32 v56, v55, v55
	v_fmac_f32_e32 v54, v41, v41
	v_fmamk_f32 v55, v40, 0xbc800000, v117
	v_fmamk_f32 v57, v40, 0xbc800000, v115
	v_add_f32_e32 v41, v56, v54
	v_fmamk_f32 v54, v40, 0xbc800000, v116
	v_fmamk_f32 v56, v40, 0xbc800000, v114
	v_mul_f32_e32 v57, v57, v57
	v_mul_f32_e32 v55, v55, v55
	v_fmac_f32_e32 v57, v56, v56
	v_fmac_f32_e32 v55, v54, v54
	v_add_f32_e32 v54, v57, v55
	v_fmamk_f32 v55, v40, 0xbc800000, v101
	v_fmamk_f32 v57, v40, 0xbc800000, v99
	v_add_f32_e32 v41, v41, v54
	v_fmamk_f32 v54, v40, 0xbc800000, v100
	v_fmamk_f32 v56, v40, 0xbc800000, v98
	v_mul_f32_e32 v57, v57, v57
	v_mul_f32_e32 v55, v55, v55
	v_fmac_f32_e32 v57, v56, v56
	v_fmac_f32_e32 v55, v54, v54
	v_add_f32_e32 v54, v57, v55
	v_fmamk_f32 v55, v40, 0xbc800000, v97
	v_fmamk_f32 v57, v40, 0xbc800000, v95
	v_add_f32_e32 v41, v54, v41
	v_fmamk_f32 v54, v40, 0xbc800000, v96
	v_fmamk_f32 v56, v40, 0xbc800000, v94
	v_mul_f32_e32 v57, v57, v57
	v_mul_f32_e32 v55, v55, v55
	v_fmac_f32_e32 v57, v56, v56
	v_fmac_f32_e32 v55, v54, v54
	v_add_f32_e32 v54, v57, v55
	v_add_f32_e32 v41, v54, v41
	v_mov_b32_e32 v54, v41
	s_nop 1
	v_permlane16_swap_b32_e32 v54, v41
	s_waitcnt lgkmcnt(0)
	v_add_f32_e32 v41, v41, v54
	v_mov_b32_e32 v54, v41
	s_nop 1
	v_permlane32_swap_b32_e32 v54, v41
	s_and_saveexec_b64 s[0:1], vcc
	s_cbranch_execz .LBB0_1097
	s_lshl_b32 s8, s35, 11
	s_add_i32 s8, s6, s8
	v_mul_f32_e32 v40, 0x3c800000, v40
	v_add_u32_e32 v55, s8, v154
	s_waitcnt lgkmcnt(0)
	v_add_f32_e32 v41, v41, v54
	ds_write_b64 v55, v[40:41] offset:512
;     __device__ __forceinline__ bool run(const f32x4 (&v)[2][2][4][2], const Unit& u, int wr, int wc, int fr, int fq, PG8_LAS unsigned char* lds, int wid, int lane) const {
;     ...
;         for (int ai = 0; ai < 2; ++ai)
; #pragma unroll
;             for (int m = 0; m < 4; ++m) {
;                 float s = 0.f;
; #pragma unroll
;                 for (int bj = 0; bj < 2; ++bj)
; #pragma unroll
;                     for (int n = 0; n < 2; ++n) { const f32x4 x = v[ai][bj][m][n]; s += (x[0] + x[1]) + (x[2] + x[3]); }
;                 s += __shfl_xor(s, 16); s += __shfl_xor(s, 32);
;                 const float mw = s * (1.0f / 64.0f); float q = 0.f;
; #pragma unroll
;                 for (int bj = 0; bj < 2; ++bj)
; #pragma unroll
;                     for (int n = 0; n < 2; ++n) { const f32x4 d = v[ai][bj][m][n] - mw; q += (d[0] * d[0] + d[1] * d[1]) + (d[2] * d[2] + d[3] * d[3]); }
;                 q += __shfl_xor(q, 16); q += __shfl_xor(q, 32);
;                 if (fq == 0) P[(ai * HALF + wr * 64 + m * 16 + fr) * 4 + wc] = (f32x2v){mw, q};
;             }
.LBB0_1097:
	s_or_b64 exec, exec, s[0:1]
	v_mov_b32_e32 v40, v91
	v_mov_b32_e32 v41, v92
	s_waitcnt lgkmcnt(0)
	v_mov_b32_e32 v54, v90
	v_mov_b32_e32 v55, v93
	v_pk_add_f32 v[40:41], v[40:41], v[54:55]
	v_mov_b32_e32 v54, v103
	v_mov_b32_e32 v55, v104
	v_mov_b32_e32 v56, v102
	v_mov_b32_e32 v57, v105
	v_pk_add_f32 v[54:55], v[54:55], v[56:57]
	v_add_f32_e32 v40, v40, v41
	v_pk_add_f32 v[54:55], v[54:55], v[54:55] op_sel_hi:[0,1]
	v_add_f32_e32 v41, 0, v40
	v_add_f32_e32 v57, v82, v83
	v_add_f32_e32 v141, v84, v85
	v_mov_b32_e32 v56, v78
	v_mov_b32_e32 v140, v79
	v_mov_b32_e32 v54, v80
	v_mov_b32_e32 v40, v81
	v_pk_add_f32 v[56:57], v[56:57], v[140:141]
	v_pk_add_f32 v[40:41], v[54:55], v[40:41]
	s_nop 0
	v_pk_add_f32 v[40:41], v[56:57], v[40:41]
	s_nop 0
	v_add_f32_e32 v40, v40, v41
	v_mov_b32_e32 v41, v40
	s_nop 1
	v_permlane16_swap_b32_e32 v41, v40
	s_waitcnt lgkmcnt(0)
	v_add_f32_e32 v40, v40, v41
	v_mov_b32_e32 v41, v40
	s_nop 1
	v_permlane32_swap_b32_e32 v41, v40
	s_waitcnt lgkmcnt(0)
	v_add_f32_e32 v40, v40, v41
	v_fmamk_f32 v54, v40, 0xbc800000, v93
	v_fmamk_f32 v56, v40, 0xbc800000, v91
	v_fmamk_f32 v41, v40, 0xbc800000, v92
	v_fmamk_f32 v55, v40, 0xbc800000, v90
	v_mul_f32_e32 v56, v56, v56
	v_mul_f32_e32 v54, v54, v54
	v_fmac_f32_e32 v56, v55, v55
	v_fmac_f32_e32 v54, v41, v41
	v_fmamk_f32 v55, v40, 0xbc800000, v105
	v_fmamk_f32 v57, v40, 0xbc800000, v103
	v_add_f32_e32 v41, v56, v54
	v_fmamk_f32 v54, v40, 0xbc800000, v104
	v_fmamk_f32 v56, v40, 0xbc800000, v102
	v_mul_f32_e32 v57, v57, v57
	v_mul_f32_e32 v55, v55, v55
	v_fmac_f32_e32 v57, v56, v56
	v_fmac_f32_e32 v55, v54, v54
	v_add_f32_e32 v54, v57, v55
	v_fmamk_f32 v55, v40, 0xbc800000, v85
	v_fmamk_f32 v57, v40, 0xbc800000, v83
	v_add_f32_e32 v41, v41, v54
	v_fmamk_f32 v54, v40, 0xbc800000, v84
	v_fmamk_f32 v56, v40, 0xbc800000, v82
	v_mul_f32_e32 v57, v57, v57
	v_mul_f32_e32 v55, v55, v55
	v_fmac_f32_e32 v57, v56, v56
	v_fmac_f32_e32 v55, v54, v54
	v_add_f32_e32 v54, v57, v55
	v_fmamk_f32 v55, v40, 0xbc800000, v81
	v_fmamk_f32 v57, v40, 0xbc800000, v79
	v_add_f32_e32 v41, v54, v41
	v_fmamk_f32 v54, v40, 0xbc800000, v80
	v_fmamk_f32 v56, v40, 0xbc800000, v78
	v_mul_f32_e32 v57, v57, v57
	v_mul_f32_e32 v55, v55, v55
	v_fmac_f32_e32 v57, v56, v56
	v_fmac_f32_e32 v55, v54, v54
	v_add_f32_e32 v54, v57, v55
	v_add_f32_e32 v41, v54, v41
	v_mov_b32_e32 v54, v41
	s_nop 1
	v_permlane16_swap_b32_e32 v54, v41
	s_waitcnt lgkmcnt(0)
	v_add_f32_e32 v41, v41, v54
	v_mov_b32_e32 v54, v41
	s_nop 1
	v_permlane32_swap_b32_e32 v54, v41
	s_and_saveexec_b64 s[0:1], vcc
	s_cbranch_execz .LBB0_1099
	s_lshl_b32 s8, s35, 11
	s_add_i32 s8, s6, s8
	v_mul_f32_e32 v40, 0x3c800000, v40
	v_add_u32_e32 v55, s8, v154
	s_waitcnt lgkmcnt(0)
	v_add_f32_e32 v41, v41, v54
	ds_write_b64 v55, v[40:41] offset:1024
.LBB0_1099:
	s_or_b64 exec, exec, s[0:1]
	v_mov_b32_e32 v40, v75
	v_mov_b32_e32 v41, v76
	s_waitcnt lgkmcnt(0)
	v_mov_b32_e32 v54, v74
	v_mov_b32_e32 v55, v77
	v_pk_add_f32 v[40:41], v[40:41], v[54:55]
	v_mov_b32_e32 v54, v87
	v_mov_b32_e32 v55, v88
	v_mov_b32_e32 v56, v86
	v_mov_b32_e32 v57, v89
	v_pk_add_f32 v[54:55], v[54:55], v[56:57]
	v_add_f32_e32 v40, v40, v41
	v_pk_add_f32 v[54:55], v[54:55], v[54:55] op_sel_hi:[0,1]
	v_add_f32_e32 v41, 0, v40
	v_add_f32_e32 v57, v70, v71
	v_add_f32_e32 v141, v72, v73
	v_mov_b32_e32 v56, v66
	v_mov_b32_e32 v140, v67
	v_mov_b32_e32 v54, v68
	v_mov_b32_e32 v40, v69
	v_pk_add_f32 v[56:57], v[56:57], v[140:141]
	v_pk_add_f32 v[40:41], v[54:55], v[40:41]
	s_nop 0
	v_pk_add_f32 v[40:41], v[56:57], v[40:41]
	s_nop 0
	v_add_f32_e32 v40, v40, v41
	v_mov_b32_e32 v41, v40
	s_nop 1
	v_permlane16_swap_b32_e32 v41, v40
	s_waitcnt lgkmcnt(0)
	v_add_f32_e32 v40, v40, v41
	v_mov_b32_e32 v41, v40
	s_nop 1
	v_permlane32_swap_b32_e32 v41, v40
	s_waitcnt lgkmcnt(0)
	v_add_f32_e32 v40, v40, v41
	v_fmamk_f32 v54, v40, 0xbc800000, v77
	v_fmamk_f32 v56, v40, 0xbc800000, v75
	v_fmamk_f32 v41, v40, 0xbc800000, v76
	v_fmamk_f32 v55, v40, 0xbc800000, v74
	v_mul_f32_e32 v56, v56, v56
	v_mul_f32_e32 v54, v54, v54
	v_fmac_f32_e32 v56, v55, v55
	v_fmac_f32_e32 v54, v41, v41
	v_fmamk_f32 v55, v40, 0xbc800000, v89
	v_fmamk_f32 v57, v40, 0xbc800000, v87
	v_add_f32_e32 v41, v56, v54
	v_fmamk_f32 v54, v40, 0xbc800000, v88
	v_fmamk_f32 v56, v40, 0xbc800000, v86
	v_mul_f32_e32 v57, v57, v57
	v_mul_f32_e32 v55, v55, v55
	v_fmac_f32_e32 v57, v56, v56
	v_fmac_f32_e32 v55, v54, v54
	v_add_f32_e32 v54, v57, v55
	v_fmamk_f32 v55, v40, 0xbc800000, v73
	v_fmamk_f32 v57, v40, 0xbc800000, v71
	v_add_f32_e32 v41, v41, v54
	v_fmamk_f32 v54, v40, 0xbc800000, v72
	v_fmamk_f32 v56, v40, 0xbc800000, v70
	v_mul_f32_e32 v57, v57, v57
	v_mul_f32_e32 v55, v55, v55
	v_fmac_f32_e32 v57, v56, v56
	v_fmac_f32_e32 v55, v54, v54
	v_add_f32_e32 v54, v57, v55
	v_fmamk_f32 v55, v40, 0xbc800000, v69
	v_fmamk_f32 v57, v40, 0xbc800000, v67
	v_add_f32_e32 v41, v54, v41
	v_fmamk_f32 v54, v40, 0xbc800000, v68
	v_fmamk_f32 v56, v40, 0xbc800000, v66
	v_mul_f32_e32 v57, v57, v57
	v_mul_f32_e32 v55, v55, v55
	v_fmac_f32_e32 v57, v56, v56
	v_fmac_f32_e32 v55, v54, v54
	v_add_f32_e32 v54, v57, v55
	v_add_f32_e32 v41, v54, v41
	v_mov_b32_e32 v54, v41
	s_nop 1
	v_permlane16_swap_b32_e32 v54, v41
	s_waitcnt lgkmcnt(0)
	v_add_f32_e32 v41, v41, v54
	v_mov_b32_e32 v54, v41
	s_nop 1
	v_permlane32_swap_b32_e32 v54, v41
	s_and_saveexec_b64 s[0:1], vcc
	s_cbranch_execz .LBB0_1101
	s_lshl_b32 s8, s35, 11
	s_add_i32 s8, s6, s8
	v_mul_f32_e32 v40, 0x3c800000, v40
	v_add_u32_e32 v55, s8, v154
	s_waitcnt lgkmcnt(0)
	v_add_f32_e32 v41, v41, v54
	ds_write_b64 v55, v[40:41] offset:1536
;     __device__ __forceinline__ bool run(const f32x4 (&v)[2][2][4][2], const Unit& u, int wr, int wc, int fr, int fq, PG8_LAS unsigned char* lds, int wid, int lane) const {
;     ...
;         for (int ai = 0; ai < 2; ++ai)
; #pragma unroll
;             for (int m = 0; m < 4; ++m) {
;                 float s = 0.f;
; #pragma unroll
;                 for (int bj = 0; bj < 2; ++bj)
; #pragma unroll
;                     for (int n = 0; n < 2; ++n) { const f32x4 x = v[ai][bj][m][n]; s += (x[0] + x[1]) + (x[2] + x[3]); }
;                 s += __shfl_xor(s, 16); s += __shfl_xor(s, 32);
;                 const float mw = s * (1.0f / 64.0f); float q = 0.f;
; #pragma unroll
;                 for (int bj = 0; bj < 2; ++bj)
; #pragma unroll
;                     for (int n = 0; n < 2; ++n) { const f32x4 d = v[ai][bj][m][n] - mw; q += (d[0] * d[0] + d[1] * d[1]) + (d[2] * d[2] + d[3] * d[3]); }
;                 q += __shfl_xor(q, 16); q += __shfl_xor(q, 32);
;                 if (fq == 0) P[(ai * HALF + wr * 64 + m * 16 + fr) * 4 + wc] = (f32x2v){mw, q};
;             }
.LBB0_1101:
	s_or_b64 exec, exec, s[0:1]
	v_mov_b32_e32 v40, v111
	v_mov_b32_e32 v41, v112
	s_waitcnt lgkmcnt(0)
	v_mov_b32_e32 v54, v110
	v_mov_b32_e32 v55, v113
	v_pk_add_f32 v[40:41], v[40:41], v[54:55]
	v_mov_b32_e32 v54, v135
	v_mov_b32_e32 v55, v136
	v_mov_b32_e32 v56, v134
	v_mov_b32_e32 v57, v137
	v_pk_add_f32 v[54:55], v[54:55], v[56:57]
	v_add_f32_e32 v40, v40, v41
	v_pk_add_f32 v[54:55], v[54:55], v[54:55] op_sel_hi:[0,1]
	v_add_f32_e32 v41, 0, v40
	v_add_f32_e32 v57, v62, v63
	v_add_f32_e32 v141, v64, v65
	v_mov_b32_e32 v56, v58
	v_mov_b32_e32 v140, v59
	v_mov_b32_e32 v54, v60
	v_mov_b32_e32 v40, v61
	v_pk_add_f32 v[56:57], v[56:57], v[140:141]
	v_pk_add_f32 v[40:41], v[54:55], v[40:41]
	s_nop 0
	v_pk_add_f32 v[40:41], v[56:57], v[40:41]
	s_nop 0
	v_add_f32_e32 v40, v40, v41
	v_mov_b32_e32 v41, v40
	s_nop 1
	v_permlane16_swap_b32_e32 v41, v40
	s_waitcnt lgkmcnt(0)
	v_add_f32_e32 v40, v40, v41
	v_mov_b32_e32 v41, v40
	s_nop 1
	v_permlane32_swap_b32_e32 v41, v40
	s_waitcnt lgkmcnt(0)
	v_add_f32_e32 v40, v40, v41
	v_fmamk_f32 v54, v40, 0xbc800000, v113
	v_fmamk_f32 v56, v40, 0xbc800000, v111
	v_fmamk_f32 v41, v40, 0xbc800000, v112
	v_fmamk_f32 v55, v40, 0xbc800000, v110
	v_mul_f32_e32 v56, v56, v56
	v_mul_f32_e32 v54, v54, v54
	v_fmac_f32_e32 v56, v55, v55
	v_fmac_f32_e32 v54, v41, v41
	v_fmamk_f32 v55, v40, 0xbc800000, v137
	v_fmamk_f32 v57, v40, 0xbc800000, v135
	v_add_f32_e32 v41, v56, v54
	v_fmamk_f32 v54, v40, 0xbc800000, v136
	v_fmamk_f32 v56, v40, 0xbc800000, v134
	v_mul_f32_e32 v57, v57, v57
	v_mul_f32_e32 v55, v55, v55
	v_fmac_f32_e32 v57, v56, v56
	v_fmac_f32_e32 v55, v54, v54
	v_add_f32_e32 v54, v57, v55
	v_fmamk_f32 v55, v40, 0xbc800000, v65
	v_fmamk_f32 v57, v40, 0xbc800000, v63
	v_add_f32_e32 v41, v41, v54
	v_fmamk_f32 v54, v40, 0xbc800000, v64
	v_fmamk_f32 v56, v40, 0xbc800000, v62
	v_mul_f32_e32 v57, v57, v57
	v_mul_f32_e32 v55, v55, v55
	v_fmac_f32_e32 v57, v56, v56
	v_fmac_f32_e32 v55, v54, v54
	v_add_f32_e32 v54, v57, v55
	v_fmamk_f32 v55, v40, 0xbc800000, v61
	v_fmamk_f32 v57, v40, 0xbc800000, v59
	v_add_f32_e32 v41, v54, v41
	v_fmamk_f32 v54, v40, 0xbc800000, v60
	v_fmamk_f32 v56, v40, 0xbc800000, v58
	v_mul_f32_e32 v57, v57, v57
	v_mul_f32_e32 v55, v55, v55
	v_fmac_f32_e32 v57, v56, v56
	v_fmac_f32_e32 v55, v54, v54
	v_add_f32_e32 v54, v57, v55
	v_add_f32_e32 v41, v54, v41
	v_mov_b32_e32 v54, v41
	s_nop 1
	v_permlane16_swap_b32_e32 v54, v41
	s_waitcnt lgkmcnt(0)
	v_add_f32_e32 v41, v41, v54
	v_mov_b32_e32 v54, v41
	s_nop 1
	v_permlane32_swap_b32_e32 v54, v41
	s_and_saveexec_b64 s[0:1], vcc
	s_cbranch_execz .LBB0_1103
	s_lshl_b32 s8, s35, 11
	s_add_i32 s8, s6, s8
	v_mul_f32_e32 v40, 0x3c800000, v40
	v_add_u32_e32 v55, s8, v154
	s_waitcnt lgkmcnt(0)
	v_add_f32_e32 v41, v41, v54
	ds_write_b64 v55, v[40:41] offset:4096
.LBB0_1103:
	s_or_b64 exec, exec, s[0:1]
	v_mov_b32_e32 v40, v51
	v_mov_b32_e32 v41, v52
	s_waitcnt lgkmcnt(0)
	v_mov_b32_e32 v54, v50
	v_mov_b32_e32 v55, v53
	v_pk_add_f32 v[40:41], v[40:41], v[54:55]
	v_mov_b32_e32 v54, v47
	v_mov_b32_e32 v55, v48
	v_mov_b32_e32 v56, v46
	v_mov_b32_e32 v57, v49
	v_pk_add_f32 v[54:55], v[54:55], v[56:57]
	v_add_f32_e32 v40, v40, v41
	v_pk_add_f32 v[54:55], v[54:55], v[54:55] op_sel_hi:[0,1]
	v_add_f32_e32 v41, 0, v40
	v_add_f32_e32 v57, v42, v43
	v_add_f32_e32 v141, v44, v45
	v_mov_b32_e32 v56, v34
	v_mov_b32_e32 v140, v35
	v_mov_b32_e32 v54, v36
	v_mov_b32_e32 v40, v37
	v_pk_add_f32 v[56:57], v[56:57], v[140:141]
	v_pk_add_f32 v[40:41], v[54:55], v[40:41]
	s_nop 0
	v_pk_add_f32 v[40:41], v[56:57], v[40:41]
	s_nop 0
	v_add_f32_e32 v40, v40, v41
	v_mov_b32_e32 v41, v40
	s_nop 1
	v_permlane16_swap_b32_e32 v41, v40
	s_waitcnt lgkmcnt(0)
	v_add_f32_e32 v40, v40, v41
	v_mov_b32_e32 v41, v40
	s_nop 1
	v_permlane32_swap_b32_e32 v41, v40
	s_waitcnt lgkmcnt(0)
	v_add_f32_e32 v40, v40, v41
	v_fmamk_f32 v54, v40, 0xbc800000, v53
	v_fmamk_f32 v56, v40, 0xbc800000, v51
	v_fmamk_f32 v41, v40, 0xbc800000, v52
	v_fmamk_f32 v55, v40, 0xbc800000, v50
	v_mul_f32_e32 v56, v56, v56
	v_mul_f32_e32 v54, v54, v54
	v_fmac_f32_e32 v56, v55, v55
	v_fmac_f32_e32 v54, v41, v41
	v_fmamk_f32 v55, v40, 0xbc800000, v49
	v_fmamk_f32 v57, v40, 0xbc800000, v47
	v_add_f32_e32 v41, v56, v54
	v_fmamk_f32 v54, v40, 0xbc800000, v48
	v_fmamk_f32 v56, v40, 0xbc800000, v46
	v_mul_f32_e32 v57, v57, v57
	v_mul_f32_e32 v55, v55, v55
	v_fmac_f32_e32 v57, v56, v56
	v_fmac_f32_e32 v55, v54, v54
	v_add_f32_e32 v54, v57, v55
	v_fmamk_f32 v55, v40, 0xbc800000, v45
	v_fmamk_f32 v57, v40, 0xbc800000, v43
	v_add_f32_e32 v41, v41, v54
	v_fmamk_f32 v54, v40, 0xbc800000, v44
	v_fmamk_f32 v56, v40, 0xbc800000, v42
	v_mul_f32_e32 v57, v57, v57
	v_mul_f32_e32 v55, v55, v55
	v_fmac_f32_e32 v57, v56, v56
	v_fmac_f32_e32 v55, v54, v54
	v_add_f32_e32 v54, v57, v55
	v_fmamk_f32 v55, v40, 0xbc800000, v37
	v_fmamk_f32 v57, v40, 0xbc800000, v35
	v_add_f32_e32 v41, v54, v41
	v_fmamk_f32 v54, v40, 0xbc800000, v36
	v_fmamk_f32 v56, v40, 0xbc800000, v34
	v_mul_f32_e32 v57, v57, v57
	v_mul_f32_e32 v55, v55, v55
	v_fmac_f32_e32 v57, v56, v56
	v_fmac_f32_e32 v55, v54, v54
	v_add_f32_e32 v54, v57, v55
	v_add_f32_e32 v41, v54, v41
	v_mov_b32_e32 v54, v41
	s_nop 1
	v_permlane16_swap_b32_e32 v54, v41
	s_waitcnt lgkmcnt(0)
	v_add_f32_e32 v41, v41, v54
	v_mov_b32_e32 v54, v41
	s_nop 1
	v_permlane32_swap_b32_e32 v54, v41
	s_and_saveexec_b64 s[0:1], vcc
	s_cbranch_execz .LBB0_1105
	s_lshl_b32 s8, s35, 11
	s_add_i32 s8, s6, s8
	v_mul_f32_e32 v40, 0x3c800000, v40
	v_add_u32_e32 v55, s8, v154
	s_waitcnt lgkmcnt(0)
	v_add_f32_e32 v41, v41, v54
	ds_write_b64 v55, v[40:41] offset:4608
;     __device__ __forceinline__ bool run(const f32x4 (&v)[2][2][4][2], const Unit& u, int wr, int wc, int fr, int fq, PG8_LAS unsigned char* lds, int wid, int lane) const {
;     ...
;         for (int ai = 0; ai < 2; ++ai)
; #pragma unroll
;             for (int m = 0; m < 4; ++m) {
;                 float s = 0.f;
; #pragma unroll
;                 for (int bj = 0; bj < 2; ++bj)
; #pragma unroll
;                     for (int n = 0; n < 2; ++n) { const f32x4 x = v[ai][bj][m][n]; s += (x[0] + x[1]) + (x[2] + x[3]); }
;                 s += __shfl_xor(s, 16); s += __shfl_xor(s, 32);
;                 const float mw = s * (1.0f / 64.0f); float q = 0.f;
; #pragma unroll
;                 for (int bj = 0; bj < 2; ++bj)
; #pragma unroll
;                     for (int n = 0; n < 2; ++n) { const f32x4 d = v[ai][bj][m][n] - mw; q += (d[0] * d[0] + d[1] * d[1]) + (d[2] * d[2] + d[3] * d[3]); }
;                 q += __shfl_xor(q, 16); q += __shfl_xor(q, 32);
;                 if (fq == 0) P[(ai * HALF + wr * 64 + m * 16 + fr) * 4 + wc] = (f32x2v){mw, q};
;             }
.LBB0_1105:
	s_or_b64 exec, exec, s[0:1]
	v_mov_b32_e32 v40, v27
	v_mov_b32_e32 v41, v28
	s_waitcnt lgkmcnt(0)
	v_mov_b32_e32 v54, v26
	v_mov_b32_e32 v55, v29
	v_pk_add_f32 v[40:41], v[40:41], v[54:55]
	v_mov_b32_e32 v54, v31
	v_mov_b32_e32 v55, v32
	v_mov_b32_e32 v56, v30
	v_mov_b32_e32 v57, v33
	v_pk_add_f32 v[54:55], v[54:55], v[56:57]
	v_add_f32_e32 v40, v40, v41
	v_pk_add_f32 v[54:55], v[54:55], v[54:55] op_sel_hi:[0,1]
	v_add_f32_e32 v41, 0, v40
	v_add_f32_e32 v57, v22, v23
	v_add_f32_e32 v141, v24, v25
	v_mov_b32_e32 v56, v18
	v_mov_b32_e32 v140, v19
	v_mov_b32_e32 v54, v20
	v_mov_b32_e32 v40, v21
	v_pk_add_f32 v[56:57], v[56:57], v[140:141]
	v_pk_add_f32 v[40:41], v[54:55], v[40:41]
	s_nop 0
	v_pk_add_f32 v[40:41], v[56:57], v[40:41]
	s_nop 0
	v_add_f32_e32 v40, v40, v41
	v_mov_b32_e32 v41, v40
	s_nop 1
	v_permlane16_swap_b32_e32 v41, v40
	s_waitcnt lgkmcnt(0)
	v_add_f32_e32 v40, v40, v41
	v_mov_b32_e32 v41, v40
	s_nop 1
	v_permlane32_swap_b32_e32 v41, v40
	s_waitcnt lgkmcnt(0)
	v_add_f32_e32 v40, v40, v41
	v_fmamk_f32 v54, v40, 0xbc800000, v29
	v_fmamk_f32 v56, v40, 0xbc800000, v27
	v_fmamk_f32 v41, v40, 0xbc800000, v28
	v_fmamk_f32 v55, v40, 0xbc800000, v26
	v_mul_f32_e32 v56, v56, v56
	v_mul_f32_e32 v54, v54, v54
	v_fmac_f32_e32 v56, v55, v55
	v_fmac_f32_e32 v54, v41, v41
	v_fmamk_f32 v55, v40, 0xbc800000, v33
	v_fmamk_f32 v57, v40, 0xbc800000, v31
	v_add_f32_e32 v41, v56, v54
	v_fmamk_f32 v54, v40, 0xbc800000, v32
	v_fmamk_f32 v56, v40, 0xbc800000, v30
	v_mul_f32_e32 v57, v57, v57
	v_mul_f32_e32 v55, v55, v55
	v_fmac_f32_e32 v57, v56, v56
	v_fmac_f32_e32 v55, v54, v54
	v_add_f32_e32 v54, v57, v55
	v_fmamk_f32 v55, v40, 0xbc800000, v25
	v_fmamk_f32 v57, v40, 0xbc800000, v23
	v_add_f32_e32 v41, v41, v54
	v_fmamk_f32 v54, v40, 0xbc800000, v24
	v_fmamk_f32 v56, v40, 0xbc800000, v22
	v_mul_f32_e32 v57, v57, v57
	v_mul_f32_e32 v55, v55, v55
	v_fmac_f32_e32 v57, v56, v56
	v_fmac_f32_e32 v55, v54, v54
	v_add_f32_e32 v54, v57, v55
	v_fmamk_f32 v55, v40, 0xbc800000, v21
	v_fmamk_f32 v57, v40, 0xbc800000, v19
	v_add_f32_e32 v41, v54, v41
	v_fmamk_f32 v54, v40, 0xbc800000, v20
	v_fmamk_f32 v56, v40, 0xbc800000, v18
	v_mul_f32_e32 v57, v57, v57
	v_mul_f32_e32 v55, v55, v55
	v_fmac_f32_e32 v57, v56, v56
	v_fmac_f32_e32 v55, v54, v54
	v_add_f32_e32 v54, v57, v55
	v_add_f32_e32 v41, v54, v41
	v_mov_b32_e32 v54, v41
	s_nop 1
	v_permlane16_swap_b32_e32 v54, v41
	s_waitcnt lgkmcnt(0)
	v_add_f32_e32 v41, v41, v54
	v_mov_b32_e32 v54, v41
	s_nop 1
	v_permlane32_swap_b32_e32 v54, v41
	s_and_saveexec_b64 s[0:1], vcc
	s_cbranch_execz .LBB0_1107
	s_lshl_b32 s8, s35, 11
	s_add_i32 s8, s6, s8
	v_mul_f32_e32 v40, 0x3c800000, v40
	v_add_u32_e32 v55, s8, v154
	s_waitcnt lgkmcnt(0)
	v_add_f32_e32 v41, v41, v54
	ds_write_b64 v55, v[40:41] offset:5120
.LBB0_1107:
	s_or_b64 exec, exec, s[0:1]
	v_mov_b32_e32 v40, v15
	v_mov_b32_e32 v41, v16
	s_waitcnt lgkmcnt(0)
	v_mov_b32_e32 v54, v14
	v_mov_b32_e32 v55, v17
	v_pk_add_f32 v[40:41], v[40:41], v[54:55]
	v_mov_b32_e32 v54, v11
	v_mov_b32_e32 v55, v12
	v_mov_b32_e32 v56, v10
	v_mov_b32_e32 v57, v13
	v_pk_add_f32 v[54:55], v[54:55], v[56:57]
	v_add_f32_e32 v40, v40, v41
	v_pk_add_f32 v[54:55], v[54:55], v[54:55] op_sel_hi:[0,1]
	v_add_f32_e32 v41, 0, v40
	v_add_f32_e32 v57, v6, v7
	v_add_f32_e32 v141, v8, v9
	v_mov_b32_e32 v56, v2
	v_mov_b32_e32 v140, v3
	v_mov_b32_e32 v54, v4
	v_mov_b32_e32 v40, v5
	v_pk_add_f32 v[56:57], v[56:57], v[140:141]
	v_pk_add_f32 v[40:41], v[54:55], v[40:41]
	s_nop 0
	v_pk_add_f32 v[40:41], v[56:57], v[40:41]
	s_nop 0
	v_add_f32_e32 v40, v40, v41
	v_mov_b32_e32 v41, v40
	s_nop 1
	v_permlane16_swap_b32_e32 v41, v40
	s_waitcnt lgkmcnt(0)
	v_add_f32_e32 v40, v40, v41
	v_mov_b32_e32 v41, v40
	s_nop 1
	v_permlane32_swap_b32_e32 v41, v40
	s_waitcnt lgkmcnt(0)
	v_add_f32_e32 v40, v40, v41
	v_fmamk_f32 v54, v40, 0xbc800000, v17
	v_fmamk_f32 v56, v40, 0xbc800000, v15
	v_fmamk_f32 v41, v40, 0xbc800000, v16
	v_fmamk_f32 v55, v40, 0xbc800000, v14
	v_mul_f32_e32 v56, v56, v56
	v_mul_f32_e32 v54, v54, v54
	v_fmac_f32_e32 v56, v55, v55
	v_fmac_f32_e32 v54, v41, v41
	v_fmamk_f32 v55, v40, 0xbc800000, v13
	v_fmamk_f32 v57, v40, 0xbc800000, v11
	v_add_f32_e32 v41, v56, v54
	v_fmamk_f32 v54, v40, 0xbc800000, v12
	v_fmamk_f32 v56, v40, 0xbc800000, v10
	v_mul_f32_e32 v57, v57, v57
	v_mul_f32_e32 v55, v55, v55
	v_fmac_f32_e32 v57, v56, v56
	v_fmac_f32_e32 v55, v54, v54
	v_add_f32_e32 v54, v57, v55
	v_fmamk_f32 v55, v40, 0xbc800000, v9
	v_fmamk_f32 v57, v40, 0xbc800000, v7
	v_add_f32_e32 v41, v41, v54
	v_fmamk_f32 v54, v40, 0xbc800000, v8
	v_fmamk_f32 v56, v40, 0xbc800000, v6
	v_mul_f32_e32 v57, v57, v57
	v_mul_f32_e32 v55, v55, v55
	v_fmac_f32_e32 v57, v56, v56
	v_fmac_f32_e32 v55, v54, v54
	v_add_f32_e32 v54, v57, v55
	v_fmamk_f32 v55, v40, 0xbc800000, v5
	v_fmamk_f32 v57, v40, 0xbc800000, v3
	v_add_f32_e32 v41, v54, v41
	v_fmamk_f32 v54, v40, 0xbc800000, v4
	v_fmamk_f32 v56, v40, 0xbc800000, v2
	v_mul_f32_e32 v57, v57, v57
	v_mul_f32_e32 v55, v55, v55
	v_fmac_f32_e32 v57, v56, v56
	v_fmac_f32_e32 v55, v54, v54
	v_add_f32_e32 v54, v57, v55
	v_add_f32_e32 v41, v54, v41
	v_mov_b32_e32 v38, v41
	s_nop 1
	v_permlane16_swap_b32_e32 v38, v41
	s_waitcnt lgkmcnt(0)
	v_add_f32_e32 v38, v41, v38
	v_mov_b32_e32 v39, v38
	s_nop 1
	v_permlane32_swap_b32_e32 v39, v38
	s_and_saveexec_b64 s[0:1], vcc
	s_cbranch_execz .LBB0_1109
	s_lshl_b32 s8, s35, 11
	s_add_i32 s6, s6, s8
	v_mul_f32_e32 v40, 0x3c800000, v40
	v_add_u32_e32 v54, s6, v154
	s_waitcnt lgkmcnt(0)
	v_add_f32_e32 v41, v38, v39
	ds_write_b64 v54, v[40:41] offset:5632

;     __device__ __forceinline__ void fused(f32x4 (&acc)[2][2][4][2], const Unit& u, int wr, int wc, int fr, int fq, PG8_LAS unsigned char* lds, int wid, int lane) const {
;     ...
;         const int col0 = u.pn * BM + wc * 32 + 8 * fq;
; #pragma unroll
;         for (int ai = 0; ai < 2; ++ai) {
;             f32x4 bs[4][2][2];
; #pragma unroll
;             for (int m = 0; m < 4; ++m) { const size_t off = (size_t)(u.pm * BM + ai * HALF + wr * 64 + m * 16 + fr) * ldc + col0;
; #pragma unroll
;                 for (int bj = 0; bj < 2; ++bj) { if (baseb) unpack8(*(const u32x4*)(baseb + off + bj * HALF), bs[m][bj][0], bs[m][bj][1]);
;                     else { bs[m][bj][0] = *(const f32x4*)(base + off + bj * HALF); bs[m][bj][1] = *(const f32x4*)(base + off + bj * HALF + 4); } } }
;             asm volatile("" ::: "memory");
; #pragma unroll
;             for (int m = 0; m < 4; ++m) {
; #pragma unroll
;                 for (int bj = 0; bj < 2; ++bj)
; #pragma unroll
;                     for (int n = 0; n < 2; ++n) acc[ai][bj][m][n] += bs[m][bj][n] * ALPHA;
;                 asm volatile("" : "+v"(acc[ai][0][m][0]), "+v"(acc[ai][0][m][1]), "+v"(acc[ai][1][m][0]), "+v"(acc[ai][1][m][1])); }
;             asm volatile("" ::: "memory");
.LBB0_1344:
	s_lshl_b32 s0, s7, 5
	s_lshl_b32 s1, s8, 8
	s_lshl_b32 s16, s6, 8
	s_or_b32 s0, s1, s0
	v_add_u32_e32 v164, s16, v170
	v_and_or_b32 v162, v150, 24, s0
	v_ashrrev_i32_e32 v165, 31, v164
	v_ashrrev_i32_e32 v163, 31, v162
	v_lshlrev_b64 v[130:131], 10, v[164:165]
	v_lshl_add_u64 v[168:169], v[130:131], 0, v[162:163]
	v_lshl_add_u64 v[134:135], v[168:169], 1, s[20:21]
	s_barrier
	global_load_dwordx4 v[130:133], v[134:135], off
	global_load_dwordx4 v[136:139], v[134:135], off offset:256
	v_or_b32_e32 v134, 16, v164
	v_or_b32_e32 v148, 32, v164
	v_ashrrev_i32_e32 v135, 31, v134
	v_ashrrev_i32_e32 v149, 31, v148
	v_or_b32_e32 v156, 48, v164
	v_lshlrev_b64 v[140:141], 11, v[134:135]
	v_lshlrev_b64 v[148:149], 11, v[148:149]
	v_ashrrev_i32_e32 v157, 31, v156
	v_lshlrev_b64 v[134:135], 1, v[162:163]
	v_lshl_add_u64 v[140:141], s[20:21], 0, v[140:141]
	v_lshl_add_u64 v[148:149], s[20:21], 0, v[148:149]
	v_lshlrev_b64 v[156:157], 11, v[156:157]
	v_lshl_add_u64 v[144:145], v[140:141], 0, v[134:135]
	v_lshl_add_u64 v[152:153], v[148:149], 0, v[134:135]
	v_lshl_add_u64 v[156:157], s[20:21], 0, v[156:157]
	global_load_dwordx4 v[140:143], v[144:145], off
	s_nop 0
	global_load_dwordx4 v[144:147], v[144:145], off offset:256
	s_nop 0
	global_load_dwordx4 v[148:151], v[152:153], off
	s_nop 0
	global_load_dwordx4 v[152:155], v[152:153], off offset:256
	v_lshl_add_u64 v[160:161], v[156:157], 0, v[134:135]
	global_load_dwordx4 v[156:159], v[160:161], off
	global_load_dwordx4 v[172:175], v[160:161], off offset:256
	s_mov_b32 s0, 0x3f9837f0
	s_waitcnt vmcnt(0)
	v_lshlrev_b32_e32 v160, 16, v130
	v_and_b32_e32 v161, 0xffff0000, v130
	v_lshlrev_b32_e32 v130, 16, v131
	v_and_b32_e32 v131, 0xffff0000, v131
	v_lshlrev_b32_e32 v166, 16, v132
	v_and_b32_e32 v167, 0xffff0000, v132
	v_lshlrev_b32_e32 v132, 16, v133
	v_and_b32_e32 v133, 0xffff0000, v133
	v_lshlrev_b32_e32 v178, 16, v138
	v_and_b32_e32 v179, 0xffff0000, v138
	v_lshlrev_b32_e32 v138, 16, v139
	v_and_b32_e32 v139, 0xffff0000, v139
	v_pk_fma_f32 v[124:125], v[130:131], s[0:1], v[124:125] op_sel_hi:[1,0,1]
	v_pk_fma_f32 v[132:133], v[132:133], s[0:1], v[128:129] op_sel_hi:[1,0,1]
	v_pk_fma_f32 v[130:131], v[166:167], s[0:1], v[126:127] op_sel_hi:[1,0,1]
	v_pk_fma_f32 v[128:129], v[138:139], s[0:1], v[104:105] op_sel_hi:[1,0,1]
	v_lshlrev_b32_e32 v180, 16, v140
	v_and_b32_e32 v181, 0xffff0000, v140
	v_lshlrev_b32_e32 v140, 16, v141
	v_and_b32_e32 v141, 0xffff0000, v141
	v_lshlrev_b32_e32 v182, 16, v142
	v_and_b32_e32 v183, 0xffff0000, v142
	v_lshlrev_b32_e32 v186, 16, v146
	v_and_b32_e32 v187, 0xffff0000, v146
	v_lshlrev_b32_e32 v188, 16, v148
	v_and_b32_e32 v189, 0xffff0000, v148
	v_lshlrev_b32_e32 v190, 16, v150
	v_and_b32_e32 v191, 0xffff0000, v150
	v_lshlrev_b32_e32 v194, 16, v154
	v_and_b32_e32 v195, 0xffff0000, v154
	v_lshlrev_b32_e32 v196, 16, v156
	v_and_b32_e32 v197, 0xffff0000, v156
	v_lshlrev_b32_e32 v142, 16, v143
	v_and_b32_e32 v143, 0xffff0000, v143
	v_lshlrev_b32_e32 v146, 16, v147
	v_and_b32_e32 v147, 0xffff0000, v147
	v_lshlrev_b32_e32 v148, 16, v149
	v_and_b32_e32 v149, 0xffff0000, v149
	v_pk_fma_f32 v[126:127], v[178:179], s[0:1], v[102:103] op_sel_hi:[1,0,1]
	v_pk_fma_f32 v[104:105], v[140:141], s[0:1], v[120:121] op_sel_hi:[1,0,1]
	v_pk_fma_f32 v[102:103], v[180:181], s[0:1], v[118:119] op_sel_hi:[1,0,1]
	v_pk_fma_f32 v[118:119], v[182:183], s[0:1], v[106:107] op_sel_hi:[1,0,1]
	v_pk_fma_f32 v[106:107], v[186:187], s[0:1], v[86:87] op_sel_hi:[1,0,1]
	v_pk_fma_f32 v[86:87], v[188:189], s[0:1], v[98:99] op_sel_hi:[1,0,1]
	v_pk_fma_f32 v[98:99], v[190:191], s[0:1], v[90:91] op_sel_hi:[1,0,1]
	v_pk_fma_f32 v[90:91], v[194:195], s[0:1], v[70:71] op_sel_hi:[1,0,1]
	v_pk_fma_f32 v[70:71], v[196:197], s[0:1], v[110:111] op_sel_hi:[1,0,1]
	v_add_u32_e32 v110, 0x80, v164
	v_add_u32_e32 v140, 0x90, v164
	v_pk_fma_f32 v[120:121], v[142:143], s[0:1], v[108:109] op_sel_hi:[1,0,1]
	v_pk_fma_f32 v[108:109], v[146:147], s[0:1], v[88:89] op_sel_hi:[1,0,1]
	v_pk_fma_f32 v[88:89], v[148:149], s[0:1], v[100:101] op_sel_hi:[1,0,1]
	v_ashrrev_i32_e32 v111, 31, v110
	v_ashrrev_i32_e32 v141, 31, v140
	v_add_u32_e32 v148, 0xa0, v164
	v_lshlrev_b32_e32 v176, 16, v136
	v_and_b32_e32 v177, 0xffff0000, v136
	v_lshlrev_b32_e32 v136, 16, v137
	v_and_b32_e32 v137, 0xffff0000, v137
	v_lshlrev_b32_e32 v184, 16, v144
	v_and_b32_e32 v185, 0xffff0000, v144
	v_lshlrev_b32_e32 v144, 16, v145
	v_and_b32_e32 v145, 0xffff0000, v145
	v_lshlrev_b32_e32 v150, 16, v151
	v_and_b32_e32 v151, 0xffff0000, v151
	v_lshlrev_b32_e32 v192, 16, v152
	v_and_b32_e32 v193, 0xffff0000, v152
	v_lshlrev_b32_e32 v152, 16, v153
	v_and_b32_e32 v153, 0xffff0000, v153
	v_lshlrev_b32_e32 v154, 16, v155
	v_and_b32_e32 v155, 0xffff0000, v155
	v_lshlrev_b32_e32 v156, 16, v157
	v_and_b32_e32 v157, 0xffff0000, v157
	v_lshlrev_b32_e32 v198, 16, v158
	v_and_b32_e32 v199, 0xffff0000, v158
	v_lshlrev_b32_e32 v158, 16, v159
	v_and_b32_e32 v159, 0xffff0000, v159
	v_lshlrev_b32_e32 v200, 16, v174
	v_and_b32_e32 v201, 0xffff0000, v174
	v_lshlrev_b32_e32 v174, 16, v175
	v_and_b32_e32 v175, 0xffff0000, v175
	v_lshlrev_b32_e32 v202, 16, v172
	v_and_b32_e32 v203, 0xffff0000, v172
	v_lshlrev_b32_e32 v172, 16, v173
	v_and_b32_e32 v173, 0xffff0000, v173
	v_lshlrev_b64 v[110:111], 10, v[110:111]
	v_lshlrev_b64 v[140:141], 11, v[140:141]
	v_ashrrev_i32_e32 v149, 31, v148
	v_pk_fma_f32 v[122:123], v[160:161], s[0:1], v[122:123] op_sel_hi:[1,0,1]
	v_pk_fma_f32 v[116:117], v[136:137], s[0:1], v[116:117] op_sel_hi:[1,0,1]
	v_pk_fma_f32 v[114:115], v[176:177], s[0:1], v[114:115] op_sel_hi:[1,0,1]
	v_pk_fma_f32 v[96:97], v[144:145], s[0:1], v[96:97] op_sel_hi:[1,0,1]
;     __device__ __forceinline__ bool run(const f32x4 (&v)[2][2][4][2], const Unit& u, int wr, int wc, int fr, int fq, PG8_LAS unsigned char* lds, int wid, int lane) const {
;     ...
;         for (int ai = 0; ai < 2; ++ai)
; #pragma unroll
;             for (int m = 0; m < 4; ++m) {
;                 float s = 0.f;
; #pragma unroll
;                 for (int bj = 0; bj < 2; ++bj)
; #pragma unroll
;                     for (int n = 0; n < 2; ++n) { const f32x4 x = v[ai][bj][m][n]; s += (x[0] + x[1]) + (x[2] + x[3]); }
;                 s += __shfl_xor(s, 16); s += __shfl_xor(s, 32);
;     __device__ __forceinline__ void fused(f32x4 (&acc)[2][2][4][2], const Unit& u, int wr, int wc, int fr, int fq, PG8_LAS unsigned char* lds, int wid, int lane) const {
;     ...
;         for (int ai = 0; ai < 2; ++ai) {
;             f32x4 bs[4][2][2];
; #pragma unroll
;             for (int m = 0; m < 4; ++m) { const size_t off = (size_t)(u.pm * BM + ai * HALF + wr * 64 + m * 16 + fr) * ldc + col0;
; #pragma unroll
;                 for (int bj = 0; bj < 2; ++bj) { if (baseb) unpack8(*(const u32x4*)(baseb + off + bj * HALF), bs[m][bj][0], bs[m][bj][1]);
;                     else { bs[m][bj][0] = *(const f32x4*)(base + off + bj * HALF); bs[m][bj][1] = *(const f32x4*)(base + off + bj * HALF + 4); } } }
;             asm volatile("" ::: "memory");
; #pragma unroll
;             for (int m = 0; m < 4; ++m) {
; #pragma unroll
;                 for (int bj = 0; bj < 2; ++bj)
; #pragma unroll
;                     for (int n = 0; n < 2; ++n) acc[ai][bj][m][n] += bs[m][bj][n] * ALPHA;
;                 asm volatile("" : "+v"(acc[ai][0][m][0]), "+v"(acc[ai][0][m][1]), "+v"(acc[ai][1][m][0]), "+v"(acc[ai][1][m][1])); }
;             asm volatile("" ::: "memory");
	v_pk_fma_f32 v[94:95], v[184:185], s[0:1], v[94:95] op_sel_hi:[1,0,1]
	v_pk_fma_f32 v[100:101], v[150:151], s[0:1], v[92:93] op_sel_hi:[1,0,1]
	v_pk_fma_f32 v[80:81], v[152:153], s[0:1], v[80:81] op_sel_hi:[1,0,1]
	v_pk_fma_f32 v[78:79], v[192:193], s[0:1], v[78:79] op_sel_hi:[1,0,1]
	v_pk_fma_f32 v[92:93], v[154:155], s[0:1], v[72:73] op_sel_hi:[1,0,1]
	v_pk_fma_f32 v[72:73], v[156:157], s[0:1], v[112:113] op_sel_hi:[1,0,1]
	v_pk_fma_f32 v[84:85], v[158:159], s[0:1], v[84:85] op_sel_hi:[1,0,1]
	v_pk_fma_f32 v[82:83], v[198:199], s[0:1], v[82:83] op_sel_hi:[1,0,1]
	v_pk_fma_f32 v[68:69], v[172:173], s[0:1], v[68:69] op_sel_hi:[1,0,1]
	v_pk_fma_f32 v[66:67], v[202:203], s[0:1], v[66:67] op_sel_hi:[1,0,1]
	v_pk_fma_f32 v[76:77], v[174:175], s[0:1], v[76:77] op_sel_hi:[1,0,1]
	v_pk_fma_f32 v[74:75], v[200:201], s[0:1], v[74:75] op_sel_hi:[1,0,1]
	v_lshl_add_u64 v[166:167], v[110:111], 0, v[162:163]
	v_lshl_add_u64 v[140:141], s[20:21], 0, v[140:141]
	v_lshlrev_b64 v[148:149], 11, v[148:149]
	v_lshl_add_u64 v[136:137], v[166:167], 1, s[20:21]
	v_lshl_add_u64 v[144:145], v[140:141], 0, v[134:135]
	v_lshl_add_u64 v[148:149], s[20:21], 0, v[148:149]
	global_load_dwordx4 v[110:113], v[136:137], off
	s_nop 0
	global_load_dwordx4 v[136:139], v[136:137], off offset:256
	s_nop 0
	global_load_dwordx4 v[140:143], v[144:145], off
	s_nop 0
	global_load_dwordx4 v[144:147], v[144:145], off offset:256
	v_lshl_add_u64 v[152:153], v[148:149], 0, v[134:135]
	global_load_dwordx4 v[148:151], v[152:153], off
	s_nop 0
	global_load_dwordx4 v[152:155], v[152:153], off offset:256
	v_add_u32_e32 v156, 0xb0, v164
	v_ashrrev_i32_e32 v157, 31, v156
	v_lshlrev_b64 v[156:157], 11, v[156:157]
	v_lshl_add_u64 v[156:157], s[20:21], 0, v[156:157]
	v_lshl_add_u64 v[134:135], v[156:157], 0, v[134:135]
	global_load_dwordx4 v[156:159], v[134:135], off
	global_load_dwordx4 v[172:175], v[134:135], off offset:256
	s_waitcnt vmcnt(7)
	v_lshlrev_b32_e32 v160, 16, v110
	v_and_b32_e32 v161, 0xffff0000, v110
	v_lshlrev_b32_e32 v110, 16, v111
	v_and_b32_e32 v111, 0xffff0000, v111
	v_lshlrev_b32_e32 v176, 16, v112
	v_and_b32_e32 v177, 0xffff0000, v112
	s_waitcnt vmcnt(6)
	v_lshlrev_b32_e32 v182, 16, v138
	v_and_b32_e32 v183, 0xffff0000, v138
	s_waitcnt vmcnt(5)
	v_lshlrev_b32_e32 v186, 16, v140
	v_and_b32_e32 v187, 0xffff0000, v140
	v_lshlrev_b32_e32 v190, 16, v142
	v_and_b32_e32 v191, 0xffff0000, v142
	s_waitcnt vmcnt(4)
	v_lshlrev_b32_e32 v198, 16, v146
	v_and_b32_e32 v199, 0xffff0000, v146
	s_waitcnt vmcnt(3)
	v_lshlrev_b32_e32 v202, 16, v148
	v_and_b32_e32 v203, 0xffff0000, v148
	v_pk_fma_f32 v[64:65], v[110:111], s[0:1], v[64:65] op_sel_hi:[1,0,1]
	v_pk_fma_f32 v[110:111], v[176:177], s[0:1], v[58:59] op_sel_hi:[1,0,1]
	v_pk_fma_f32 v[58:59], v[182:183], s[0:1], v[42:43] op_sel_hi:[1,0,1]
	v_pk_fma_f32 v[42:43], v[186:187], s[0:1], v[54:55] op_sel_hi:[1,0,1]
	v_pk_fma_f32 v[54:55], v[190:191], s[0:1], v[46:47] op_sel_hi:[1,0,1]
	v_pk_fma_f32 v[46:47], v[198:199], s[0:1], v[26:27] op_sel_hi:[1,0,1]
	v_pk_fma_f32 v[26:27], v[202:203], s[0:1], v[38:39] op_sel_hi:[1,0,1]
	v_mbcnt_lo_u32_b32 v38, -1, 0
	v_lshlrev_b32_e32 v112, 16, v113
	v_and_b32_e32 v113, 0xffff0000, v113
	v_lshlrev_b32_e32 v184, 16, v139
	v_and_b32_e32 v185, 0xffff0000, v139
	v_lshlrev_b32_e32 v188, 16, v141
	v_and_b32_e32 v189, 0xffff0000, v141
	v_lshlrev_b32_e32 v192, 16, v143
	v_and_b32_e32 v193, 0xffff0000, v143
	v_lshlrev_b32_e32 v200, 16, v147
	v_and_b32_e32 v201, 0xffff0000, v147
	v_lshlrev_b32_e32 v148, 16, v149
	v_and_b32_e32 v149, 0xffff0000, v149
	v_mbcnt_hi_u32_b32 v39, -1, v38
	s_waitcnt vmcnt(2)
	v_lshlrev_b32_e32 v208, 16, v154
	v_and_b32_e32 v209, 0xffff0000, v154
	v_lshlrev_b32_e32 v154, 16, v155
	v_and_b32_e32 v155, 0xffff0000, v155
	v_pk_fma_f32 v[112:113], v[112:113], s[0:1], v[60:61] op_sel_hi:[1,0,1]
	v_pk_fma_f32 v[60:61], v[184:185], s[0:1], v[44:45] op_sel_hi:[1,0,1]
	v_pk_fma_f32 v[44:45], v[188:189], s[0:1], v[56:57] op_sel_hi:[1,0,1]
	v_pk_fma_f32 v[56:57], v[192:193], s[0:1], v[48:49] op_sel_hi:[1,0,1]
	v_pk_fma_f32 v[48:49], v[200:201], s[0:1], v[28:29] op_sel_hi:[1,0,1]
	v_pk_fma_f32 v[28:29], v[148:149], s[0:1], v[40:41] op_sel_hi:[1,0,1]
	v_and_b32_e32 v40, 64, v39
	v_lshlrev_b32_e32 v204, 16, v150
	v_and_b32_e32 v205, 0xffff0000, v150
	v_lshlrev_b32_e32 v150, 16, v151
	v_and_b32_e32 v151, 0xffff0000, v151
	v_pk_fma_f32 v[20:21], v[154:155], s[0:1], v[20:21] op_sel_hi:[1,0,1]
	v_add_u32_e32 v154, 64, v40
	v_mov_b32_e32 v40, v123
	v_mov_b32_e32 v41, v124
	v_mov_b32_e32 v148, v122
	v_mov_b32_e32 v149, v125
	v_pk_fma_f32 v[32:33], v[150:151], s[0:1], v[32:33] op_sel_hi:[1,0,1]
	v_pk_add_f32 v[40:41], v[40:41], v[148:149]
	v_mov_b32_e32 v148, v131
	v_mov_b32_e32 v149, v132
	v_mov_b32_e32 v150, v130
	v_mov_b32_e32 v151, v133
	v_pk_add_f32 v[148:149], v[148:149], v[150:151]
	v_lshlrev_b32_e32 v206, 16, v152
	v_and_b32_e32 v207, 0xffff0000, v152
	v_lshlrev_b32_e32 v152, 16, v153
	v_and_b32_e32 v153, 0xffff0000, v153
	v_add_f32_e32 v40, v40, v41
	v_pk_add_f32 v[148:149], v[148:149], v[148:149] op_sel_hi:[0,1]
	v_pk_fma_f32 v[24:25], v[152:153], s[0:1], v[24:25] op_sel_hi:[1,0,1]
	v_xor_b32_e32 v38, 16, v39
	v_add_f32_e32 v41, 0, v40
	v_add_f32_e32 v151, v114, v115
	v_add_f32_e32 v153, v116, v117
	v_mov_b32_e32 v150, v126
	v_mov_b32_e32 v152, v127
	v_mov_b32_e32 v148, v128
	v_mov_b32_e32 v40, v129
	v_cmp_lt_i32_e32 vcc, v38, v154
	v_pk_add_f32 v[150:151], v[150:151], v[152:153]
	v_pk_add_f32 v[40:41], v[148:149], v[40:41]
	v_cndmask_b32_e32 v38, v39, v38, vcc
	v_pk_add_f32 v[40:41], v[150:151], v[40:41]
	v_lshlrev_b32_e32 v38, 2, v38
	v_add_f32_e32 v40, v40, v41
	v_mov_b32_e32 v41, v40
	s_nop 1
	v_permlane16_swap_b32_e32 v41, v40
	v_xor_b32_e32 v148, 32, v39
	v_cmp_lt_i32_e32 vcc, v148, v154
	s_waitcnt vmcnt(1)
;     __device__ __forceinline__ bool run(const f32x4 (&v)[2][2][4][2], const Unit& u, int wr, int wc, int fr, int fq, PG8_LAS unsigned char* lds, int wid, int lane) const {
;     ...
; #pragma unroll
;         for (int ai = 0; ai < 2; ++ai)
; #pragma unroll
;             for (int m = 0; m < 4; ++m) {
;                 float s = 0.f;
; #pragma unroll
;                 for (int bj = 0; bj < 2; ++bj)
; #pragma unroll
;                     for (int n = 0; n < 2; ++n) { const f32x4 x = v[ai][bj][m][n]; s += (x[0] + x[1]) + (x[2] + x[3]); }
;                 s += __shfl_xor(s, 16); s += __shfl_xor(s, 32);
;                 const float mw = s * (1.0f / 64.0f); float q = 0.f;
; #pragma unroll
;                 for (int bj = 0; bj < 2; ++bj)
; #pragma unroll
;                     for (int n = 0; n < 2; ++n) { const f32x4 d = v[ai][bj][m][n] - mw; q += (d[0] * d[0] + d[1] * d[1]) + (d[2] * d[2] + d[3] * d[3]); }
;                 q += __shfl_xor(q, 16); q += __shfl_xor(q, 32);
;                 if (fq == 0) P[(ai * HALF + wr * 64 + m * 16 + fr) * 4 + wc] = (f32x2v){mw, q};
;     __device__ __forceinline__ void fused(f32x4 (&acc)[2][2][4][2], const Unit& u, int wr, int wc, int fr, int fq, PG8_LAS unsigned char* lds, int wid, int lane) const {
;     ...
;             for (int m = 0; m < 4; ++m) {
; #pragma unroll
;                 for (int bj = 0; bj < 2; ++bj)
; #pragma unroll
;                     for (int n = 0; n < 2; ++n) acc[ai][bj][m][n] += bs[m][bj][n] * ALPHA;
;                 asm volatile("" : "+v"(acc[ai][0][m][0]), "+v"(acc[ai][0][m][1]), "+v"(acc[ai][1][m][0]), "+v"(acc[ai][1][m][1])); }
	v_lshlrev_b32_e32 v140, 16, v156
	v_and_b32_e32 v141, 0xffff0000, v156
	v_cndmask_b32_e32 v39, v39, v148, vcc
	v_lshlrev_b32_e32 v39, 2, v39
	s_waitcnt lgkmcnt(0)
	v_add_f32_e32 v40, v40, v41
	v_mov_b32_e32 v41, v40
	s_nop 1
	v_permlane32_swap_b32_e32 v41, v40
	v_lshlrev_b32_e32 v142, 16, v158
	v_and_b32_e32 v143, 0xffff0000, v158
	v_pk_fma_f32 v[14:15], v[140:141], s[0:1], v[14:15] op_sel_hi:[1,0,1]
	v_pk_fma_f32 v[10:11], v[142:143], s[0:1], v[10:11] op_sel_hi:[1,0,1]
	s_waitcnt lgkmcnt(0)
	v_add_f32_e32 v40, v40, v41
	v_fmamk_f32 v140, v40, 0xbc800000, v125
	v_fmamk_f32 v142, v40, 0xbc800000, v123
	v_fmamk_f32 v41, v40, 0xbc800000, v124
	v_fmamk_f32 v141, v40, 0xbc800000, v122
	v_mul_f32_e32 v142, v142, v142
	v_mul_f32_e32 v140, v140, v140
	v_fmac_f32_e32 v142, v141, v141
	v_fmac_f32_e32 v140, v41, v41
	v_fmamk_f32 v141, v40, 0xbc800000, v133
	v_fmamk_f32 v143, v40, 0xbc800000, v131
	v_add_f32_e32 v41, v142, v140
	v_fmamk_f32 v140, v40, 0xbc800000, v132
	v_fmamk_f32 v142, v40, 0xbc800000, v130
	v_mul_f32_e32 v143, v143, v143
	v_mul_f32_e32 v141, v141, v141
	v_fmac_f32_e32 v143, v142, v142
	v_fmac_f32_e32 v141, v140, v140
	v_add_f32_e32 v140, v143, v141
	v_fmamk_f32 v141, v40, 0xbc800000, v117
	v_fmamk_f32 v143, v40, 0xbc800000, v115
	v_add_f32_e32 v41, v41, v140
	v_fmamk_f32 v140, v40, 0xbc800000, v116
	v_fmamk_f32 v142, v40, 0xbc800000, v114
	v_mul_f32_e32 v143, v143, v143
	v_mul_f32_e32 v141, v141, v141
	v_fmac_f32_e32 v143, v142, v142
	v_fmac_f32_e32 v141, v140, v140
	v_add_f32_e32 v140, v143, v141
	v_fmamk_f32 v141, v40, 0xbc800000, v129
	v_fmamk_f32 v143, v40, 0xbc800000, v127
	v_add_f32_e32 v41, v140, v41
	v_fmamk_f32 v140, v40, 0xbc800000, v128
	v_fmamk_f32 v142, v40, 0xbc800000, v126
	v_mul_f32_e32 v143, v143, v143
	v_mul_f32_e32 v141, v141, v141
	v_fmac_f32_e32 v143, v142, v142
	v_fmac_f32_e32 v141, v140, v140
	v_add_f32_e32 v140, v143, v141
	v_add_f32_e32 v41, v140, v41
	v_mov_b32_e32 v140, v41
	s_nop 1
	v_permlane16_swap_b32_e32 v140, v41
	s_waitcnt vmcnt(0)
	v_lshlrev_b32_e32 v134, 16, v174
	v_and_b32_e32 v135, 0xffff0000, v174
	v_lshlrev_b32_e32 v178, 16, v136
	v_and_b32_e32 v179, 0xffff0000, v136
	s_waitcnt lgkmcnt(0)
	v_add_f32_e32 v41, v41, v140
	v_lshlrev_b32_e32 v180, 16, v137
	v_and_b32_e32 v181, 0xffff0000, v137
	v_lshlrev_b32_e32 v194, 16, v144
	v_and_b32_e32 v195, 0xffff0000, v144
	v_lshlrev_b32_e32 v196, 16, v145
	v_and_b32_e32 v197, 0xffff0000, v145
	v_lshlrev_b32_e32 v156, 16, v157
	v_and_b32_e32 v157, 0xffff0000, v157
	v_lshlrev_b32_e32 v144, 16, v159
	v_and_b32_e32 v145, 0xffff0000, v159
	v_lshlrev_b32_e32 v136, 16, v175
	v_and_b32_e32 v137, 0xffff0000, v175
	v_lshlrev_b32_e32 v138, 16, v172
	v_and_b32_e32 v139, 0xffff0000, v172
	v_lshlrev_b32_e32 v146, 16, v173
	v_and_b32_e32 v147, 0xffff0000, v173
	v_pk_fma_f32 v[2:3], v[134:135], s[0:1], v[2:3] op_sel_hi:[1,0,1]
	v_mov_b32_e32 v134, v41
	s_nop 1
	v_permlane32_swap_b32_e32 v134, v41
	v_pk_fma_f32 v[62:63], v[160:161], s[0:1], v[62:63] op_sel_hi:[1,0,1]
	v_pk_fma_f32 v[52:53], v[180:181], s[0:1], v[52:53] op_sel_hi:[1,0,1]
	v_pk_fma_f32 v[50:51], v[178:179], s[0:1], v[50:51] op_sel_hi:[1,0,1]
	v_pk_fma_f32 v[36:37], v[196:197], s[0:1], v[36:37] op_sel_hi:[1,0,1]
	v_pk_fma_f32 v[34:35], v[194:195], s[0:1], v[34:35] op_sel_hi:[1,0,1]
	v_pk_fma_f32 v[30:31], v[204:205], s[0:1], v[30:31] op_sel_hi:[1,0,1]
	v_pk_fma_f32 v[22:23], v[206:207], s[0:1], v[22:23] op_sel_hi:[1,0,1]
	v_pk_fma_f32 v[18:19], v[208:209], s[0:1], v[18:19] op_sel_hi:[1,0,1]
	v_pk_fma_f32 v[16:17], v[156:157], s[0:1], v[16:17] op_sel_hi:[1,0,1]
	v_pk_fma_f32 v[12:13], v[144:145], s[0:1], v[12:13] op_sel_hi:[1,0,1]
	v_pk_fma_f32 v[8:9], v[146:147], s[0:1], v[8:9] op_sel_hi:[1,0,1]
	v_pk_fma_f32 v[6:7], v[138:139], s[0:1], v[6:7] op_sel_hi:[1,0,1]
	v_pk_fma_f32 v[4:5], v[136:137], s[0:1], v[4:5] op_sel_hi:[1,0,1]
	s_lshl_b32 s0, s7, 3
	v_cmp_gt_u32_e32 vcc, 16, v234
	s_add_i32 s2, s0, 0
	s_and_saveexec_b64 s[0:1], vcc
	s_cbranch_execz .LBB0_1346
	s_lshl_b32 s4, s9, 11
	s_add_i32 s4, s2, s4
	v_mul_f32_e32 v40, 0x3c800000, v40
	v_lshl_add_u32 v135, v1, 5, s4
	s_waitcnt lgkmcnt(0)
	v_add_f32_e32 v41, v41, v134
	ds_write_b64 v135, v[40:41]
.LBB0_1346:
	s_or_b64 exec, exec, s[0:1]
	v_mov_b32_e32 v40, v103
	v_mov_b32_e32 v41, v104
	s_waitcnt lgkmcnt(0)
	v_mov_b32_e32 v134, v102
	v_mov_b32_e32 v135, v105
	v_pk_add_f32 v[40:41], v[40:41], v[134:135]
	v_mov_b32_e32 v134, v119
	v_mov_b32_e32 v135, v120
	v_mov_b32_e32 v136, v118
	v_mov_b32_e32 v137, v121
	v_pk_add_f32 v[134:135], v[134:135], v[136:137]
	v_add_f32_e32 v40, v40, v41
	v_pk_add_f32 v[134:135], v[134:135], v[134:135] op_sel_hi:[0,1]
	v_add_f32_e32 v41, 0, v40
	v_add_f32_e32 v137, v94, v95
	v_add_f32_e32 v139, v96, v97
	v_mov_b32_e32 v136, v106
	v_mov_b32_e32 v138, v107
	v_mov_b32_e32 v134, v108
	v_mov_b32_e32 v40, v109
	v_pk_add_f32 v[136:137], v[136:137], v[138:139]
	v_pk_add_f32 v[40:41], v[134:135], v[40:41]
	s_nop 0
	v_pk_add_f32 v[40:41], v[136:137], v[40:41]
	s_nop 0
	v_add_f32_e32 v40, v40, v41
	v_mov_b32_e32 v41, v40
	s_nop 1
	v_permlane16_swap_b32_e32 v41, v40
	s_waitcnt lgkmcnt(0)
	v_add_f32_e32 v40, v40, v41
	v_mov_b32_e32 v41, v40
	s_nop 1
	v_permlane32_swap_b32_e32 v41, v40
	s_waitcnt lgkmcnt(0)
	v_add_f32_e32 v40, v40, v41
	v_fmamk_f32 v134, v40, 0xbc800000, v105
	v_fmamk_f32 v136, v40, 0xbc800000, v103
	v_fmamk_f32 v41, v40, 0xbc800000, v104
	v_fmamk_f32 v135, v40, 0xbc800000, v102
	v_mul_f32_e32 v136, v136, v136
	v_mul_f32_e32 v134, v134, v134
	v_fmac_f32_e32 v136, v135, v135
	v_fmac_f32_e32 v134, v41, v41
	v_fmamk_f32 v135, v40, 0xbc800000, v121
	v_fmamk_f32 v137, v40, 0xbc800000, v119
	v_add_f32_e32 v41, v136, v134
	v_fmamk_f32 v134, v40, 0xbc800000, v120
	v_fmamk_f32 v136, v40, 0xbc800000, v118
	v_mul_f32_e32 v137, v137, v137
	v_mul_f32_e32 v135, v135, v135
	v_fmac_f32_e32 v137, v136, v136
	v_fmac_f32_e32 v135, v134, v134
	v_add_f32_e32 v134, v137, v135
	v_fmamk_f32 v135, v40, 0xbc800000, v97
	v_fmamk_f32 v137, v40, 0xbc800000, v95
	v_add_f32_e32 v41, v41, v134
	v_fmamk_f32 v134, v40, 0xbc800000, v96
	v_fmamk_f32 v136, v40, 0xbc800000, v94
	v_mul_f32_e32 v137, v137, v137
	v_mul_f32_e32 v135, v135, v135
	v_fmac_f32_e32 v137, v136, v136
	v_fmac_f32_e32 v135, v134, v134
	v_add_f32_e32 v134, v137, v135
	v_fmamk_f32 v135, v40, 0xbc800000, v109
	v_fmamk_f32 v137, v40, 0xbc800000, v107
	v_add_f32_e32 v41, v134, v41
	v_fmamk_f32 v134, v40, 0xbc800000, v108
	v_fmamk_f32 v136, v40, 0xbc800000, v106
	v_mul_f32_e32 v137, v137, v137
	v_mul_f32_e32 v135, v135, v135
	v_fmac_f32_e32 v137, v136, v136
	v_fmac_f32_e32 v135, v134, v134
	v_add_f32_e32 v134, v137, v135
	v_add_f32_e32 v41, v134, v41
	v_mov_b32_e32 v134, v41
	s_nop 1
	v_permlane16_swap_b32_e32 v134, v41
	s_waitcnt lgkmcnt(0)
	v_add_f32_e32 v41, v41, v134
	v_mov_b32_e32 v134, v41
	s_nop 1
	v_permlane32_swap_b32_e32 v134, v41
	s_and_saveexec_b64 s[0:1], vcc
	s_cbranch_execz .LBB0_1348
;     __device__ __forceinline__ bool run(const f32x4 (&v)[2][2][4][2], const Unit& u, int wr, int wc, int fr, int fq, PG8_LAS unsigned char* lds, int wid, int lane) const {
;     ...
; #pragma unroll
;         for (int ai = 0; ai < 2; ++ai)
; #pragma unroll
;             for (int m = 0; m < 4; ++m) {
;                 float s = 0.f;
; #pragma unroll
;                 for (int bj = 0; bj < 2; ++bj)
; #pragma unroll
;                     for (int n = 0; n < 2; ++n) { const f32x4 x = v[ai][bj][m][n]; s += (x[0] + x[1]) + (x[2] + x[3]); }
;                 s += __shfl_xor(s, 16); s += __shfl_xor(s, 32);
;                 const float mw = s * (1.0f / 64.0f); float q = 0.f;
; #pragma unroll
;                 for (int bj = 0; bj < 2; ++bj)
; #pragma unroll
;                     for (int n = 0; n < 2; ++n) { const f32x4 d = v[ai][bj][m][n] - mw; q += (d[0] * d[0] + d[1] * d[1]) + (d[2] * d[2] + d[3] * d[3]); }
;                 q += __shfl_xor(q, 16); q += __shfl_xor(q, 32);
;                 if (fq == 0) P[(ai * HALF + wr * 64 + m * 16 + fr) * 4 + wc] = (f32x2v){mw, q};
	s_lshl_b32 s4, s9, 11
	s_add_i32 s4, s2, s4
	v_mul_f32_e32 v40, 0x3c800000, v40
	v_lshl_add_u32 v135, v1, 5, s4
	s_waitcnt lgkmcnt(0)
	v_add_f32_e32 v41, v41, v134
	ds_write_b64 v135, v[40:41] offset:512
.LBB0_1348:
	s_or_b64 exec, exec, s[0:1]
	v_mov_b32_e32 v40, v87
	v_mov_b32_e32 v41, v88
	s_waitcnt lgkmcnt(0)
	v_mov_b32_e32 v134, v86
	v_mov_b32_e32 v135, v89
	v_pk_add_f32 v[40:41], v[40:41], v[134:135]
	v_mov_b32_e32 v134, v99
	v_mov_b32_e32 v135, v100
	v_mov_b32_e32 v136, v98
	v_mov_b32_e32 v137, v101
	v_pk_add_f32 v[134:135], v[134:135], v[136:137]
	v_add_f32_e32 v40, v40, v41
	v_pk_add_f32 v[134:135], v[134:135], v[134:135] op_sel_hi:[0,1]
	v_add_f32_e32 v41, 0, v40
	v_add_f32_e32 v137, v78, v79
	v_add_f32_e32 v139, v80, v81
	v_mov_b32_e32 v136, v90
	v_mov_b32_e32 v138, v91
	v_mov_b32_e32 v134, v92
	v_mov_b32_e32 v40, v93
	v_pk_add_f32 v[136:137], v[136:137], v[138:139]
	v_pk_add_f32 v[40:41], v[134:135], v[40:41]
	s_nop 0
	v_pk_add_f32 v[40:41], v[136:137], v[40:41]
	s_nop 0
	v_add_f32_e32 v40, v40, v41
	v_mov_b32_e32 v41, v40
	s_nop 1
	v_permlane16_swap_b32_e32 v41, v40
	s_waitcnt lgkmcnt(0)
	v_add_f32_e32 v40, v40, v41
	v_mov_b32_e32 v41, v40
	s_nop 1
	v_permlane32_swap_b32_e32 v41, v40
	s_waitcnt lgkmcnt(0)
	v_add_f32_e32 v40, v40, v41
	v_fmamk_f32 v134, v40, 0xbc800000, v89
	v_fmamk_f32 v136, v40, 0xbc800000, v87
	v_fmamk_f32 v41, v40, 0xbc800000, v88
	v_fmamk_f32 v135, v40, 0xbc800000, v86
	v_mul_f32_e32 v136, v136, v136
	v_mul_f32_e32 v134, v134, v134
	v_fmac_f32_e32 v136, v135, v135
	v_fmac_f32_e32 v134, v41, v41
	v_fmamk_f32 v135, v40, 0xbc800000, v101
	v_fmamk_f32 v137, v40, 0xbc800000, v99
	v_add_f32_e32 v41, v136, v134
	v_fmamk_f32 v134, v40, 0xbc800000, v100
	v_fmamk_f32 v136, v40, 0xbc800000, v98
	v_mul_f32_e32 v137, v137, v137
	v_mul_f32_e32 v135, v135, v135
	v_fmac_f32_e32 v137, v136, v136
	v_fmac_f32_e32 v135, v134, v134
	v_add_f32_e32 v134, v137, v135
	v_fmamk_f32 v135, v40, 0xbc800000, v81
	v_fmamk_f32 v137, v40, 0xbc800000, v79
	v_add_f32_e32 v41, v41, v134
	v_fmamk_f32 v134, v40, 0xbc800000, v80
	v_fmamk_f32 v136, v40, 0xbc800000, v78
	v_mul_f32_e32 v137, v137, v137
	v_mul_f32_e32 v135, v135, v135
	v_fmac_f32_e32 v137, v136, v136
	v_fmac_f32_e32 v135, v134, v134
	v_add_f32_e32 v134, v137, v135
	v_fmamk_f32 v135, v40, 0xbc800000, v93
	v_fmamk_f32 v137, v40, 0xbc800000, v91
	v_add_f32_e32 v41, v134, v41
	v_fmamk_f32 v134, v40, 0xbc800000, v92
	v_fmamk_f32 v136, v40, 0xbc800000, v90
	v_mul_f32_e32 v137, v137, v137
	v_mul_f32_e32 v135, v135, v135
	v_fmac_f32_e32 v137, v136, v136
	v_fmac_f32_e32 v135, v134, v134
	v_add_f32_e32 v134, v137, v135
	v_add_f32_e32 v41, v134, v41
	v_mov_b32_e32 v134, v41
	s_nop 1
	v_permlane16_swap_b32_e32 v134, v41
	s_waitcnt lgkmcnt(0)
	v_add_f32_e32 v41, v41, v134
	v_mov_b32_e32 v134, v41
	s_nop 1
	v_permlane32_swap_b32_e32 v134, v41
	s_and_saveexec_b64 s[0:1], vcc
	s_cbranch_execz .LBB0_1350
	s_lshl_b32 s4, s9, 11
	s_add_i32 s4, s2, s4
	v_mul_f32_e32 v40, 0x3c800000, v40
	v_lshl_add_u32 v135, v1, 5, s4
	s_waitcnt lgkmcnt(0)
	v_add_f32_e32 v41, v41, v134
	ds_write_b64 v135, v[40:41] offset:1024
.LBB0_1350:
	s_or_b64 exec, exec, s[0:1]
	v_mov_b32_e32 v40, v71
	v_mov_b32_e32 v41, v72
	s_waitcnt lgkmcnt(0)
	v_mov_b32_e32 v134, v70
	v_mov_b32_e32 v135, v73
	v_pk_add_f32 v[40:41], v[40:41], v[134:135]
	v_mov_b32_e32 v134, v83
	v_mov_b32_e32 v135, v84
	v_mov_b32_e32 v136, v82
	v_mov_b32_e32 v137, v85
	v_pk_add_f32 v[134:135], v[134:135], v[136:137]
	v_add_f32_e32 v40, v40, v41
	v_pk_add_f32 v[134:135], v[134:135], v[134:135] op_sel_hi:[0,1]
	v_add_f32_e32 v41, 0, v40
	v_add_f32_e32 v137, v66, v67
	v_add_f32_e32 v139, v68, v69
	v_mov_b32_e32 v136, v74
	v_mov_b32_e32 v138, v75
	v_mov_b32_e32 v134, v76
	v_mov_b32_e32 v40, v77
	v_pk_add_f32 v[136:137], v[136:137], v[138:139]
	v_pk_add_f32 v[40:41], v[134:135], v[40:41]
	s_nop 0
	v_pk_add_f32 v[40:41], v[136:137], v[40:41]
	s_nop 0
	v_add_f32_e32 v40, v40, v41
	v_mov_b32_e32 v41, v40
	s_nop 1
	v_permlane16_swap_b32_e32 v41, v40
	s_waitcnt lgkmcnt(0)
	v_add_f32_e32 v40, v40, v41
	v_mov_b32_e32 v41, v40
	s_nop 1
	v_permlane32_swap_b32_e32 v41, v40
	s_waitcnt lgkmcnt(0)
	v_add_f32_e32 v40, v40, v41
	v_fmamk_f32 v134, v40, 0xbc800000, v73
	v_fmamk_f32 v136, v40, 0xbc800000, v71
	v_fmamk_f32 v41, v40, 0xbc800000, v72
	v_fmamk_f32 v135, v40, 0xbc800000, v70
	v_mul_f32_e32 v136, v136, v136
	v_mul_f32_e32 v134, v134, v134
	v_fmac_f32_e32 v136, v135, v135
	v_fmac_f32_e32 v134, v41, v41
	v_fmamk_f32 v135, v40, 0xbc800000, v85
	v_fmamk_f32 v137, v40, 0xbc800000, v83
	v_add_f32_e32 v41, v136, v134
	v_fmamk_f32 v134, v40, 0xbc800000, v84
	v_fmamk_f32 v136, v40, 0xbc800000, v82
	v_mul_f32_e32 v137, v137, v137
	v_mul_f32_e32 v135, v135, v135
	v_fmac_f32_e32 v137, v136, v136
	v_fmac_f32_e32 v135, v134, v134
	v_add_f32_e32 v134, v137, v135
	v_fmamk_f32 v135, v40, 0xbc800000, v69
	v_fmamk_f32 v137, v40, 0xbc800000, v67
	v_add_f32_e32 v41, v41, v134
	v_fmamk_f32 v134, v40, 0xbc800000, v68
	v_fmamk_f32 v136, v40, 0xbc800000, v66
	v_mul_f32_e32 v137, v137, v137
	v_mul_f32_e32 v135, v135, v135
	v_fmac_f32_e32 v137, v136, v136
	v_fmac_f32_e32 v135, v134, v134
	v_add_f32_e32 v134, v137, v135
	v_fmamk_f32 v135, v40, 0xbc800000, v77
	v_fmamk_f32 v137, v40, 0xbc800000, v75
	v_add_f32_e32 v41, v134, v41
	v_fmamk_f32 v134, v40, 0xbc800000, v76
	v_fmamk_f32 v136, v40, 0xbc800000, v74
	v_mul_f32_e32 v137, v137, v137
	v_mul_f32_e32 v135, v135, v135
	v_fmac_f32_e32 v137, v136, v136
	v_fmac_f32_e32 v135, v134, v134
	v_add_f32_e32 v134, v137, v135
	v_add_f32_e32 v41, v134, v41
	v_mov_b32_e32 v134, v41
	s_nop 1
	v_permlane16_swap_b32_e32 v134, v41
	s_waitcnt lgkmcnt(0)
	v_add_f32_e32 v41, v41, v134
	v_mov_b32_e32 v134, v41
	s_nop 1
	v_permlane32_swap_b32_e32 v134, v41
	s_and_saveexec_b64 s[0:1], vcc
	s_cbranch_execz .LBB0_1352
	s_lshl_b32 s4, s9, 11
	s_add_i32 s4, s2, s4
	v_mul_f32_e32 v40, 0x3c800000, v40
	v_lshl_add_u32 v135, v1, 5, s4
	s_waitcnt lgkmcnt(0)
	v_add_f32_e32 v41, v41, v134
	ds_write_b64 v135, v[40:41] offset:1536
;     __device__ __forceinline__ bool run(const f32x4 (&v)[2][2][4][2], const Unit& u, int wr, int wc, int fr, int fq, PG8_LAS unsigned char* lds, int wid, int lane) const {
;     ...
; #pragma unroll
;         for (int ai = 0; ai < 2; ++ai)
; #pragma unroll
;             for (int m = 0; m < 4; ++m) {
;                 float s = 0.f;
; #pragma unroll
;                 for (int bj = 0; bj < 2; ++bj)
; #pragma unroll
;                     for (int n = 0; n < 2; ++n) { const f32x4 x = v[ai][bj][m][n]; s += (x[0] + x[1]) + (x[2] + x[3]); }
;                 s += __shfl_xor(s, 16); s += __shfl_xor(s, 32);
;                 const float mw = s * (1.0f / 64.0f); float q = 0.f;
; #pragma unroll
;                 for (int bj = 0; bj < 2; ++bj)
; #pragma unroll
;                     for (int n = 0; n < 2; ++n) { const f32x4 d = v[ai][bj][m][n] - mw; q += (d[0] * d[0] + d[1] * d[1]) + (d[2] * d[2] + d[3] * d[3]); }
;                 q += __shfl_xor(q, 16); q += __shfl_xor(q, 32);
;                 if (fq == 0) P[(ai * HALF + wr * 64 + m * 16 + fr) * 4 + wc] = (f32x2v){mw, q};
.LBB0_1352:
	s_or_b64 exec, exec, s[0:1]
	v_mov_b32_e32 v40, v63
	v_mov_b32_e32 v41, v64
	s_waitcnt lgkmcnt(0)
	v_mov_b32_e32 v134, v62
	v_mov_b32_e32 v135, v65
	v_pk_add_f32 v[40:41], v[40:41], v[134:135]
	v_mov_b32_e32 v134, v111
	v_mov_b32_e32 v135, v112
	v_mov_b32_e32 v136, v110
	v_mov_b32_e32 v137, v113
	v_pk_add_f32 v[134:135], v[134:135], v[136:137]
	v_add_f32_e32 v40, v40, v41
	v_pk_add_f32 v[134:135], v[134:135], v[134:135] op_sel_hi:[0,1]
	v_add_f32_e32 v41, 0, v40
	v_add_f32_e32 v137, v50, v51
	v_add_f32_e32 v139, v52, v53
	v_mov_b32_e32 v136, v58
	v_mov_b32_e32 v138, v59
	v_mov_b32_e32 v134, v60
	v_mov_b32_e32 v40, v61
	v_pk_add_f32 v[136:137], v[136:137], v[138:139]
	v_pk_add_f32 v[40:41], v[134:135], v[40:41]
	s_nop 0
	v_pk_add_f32 v[40:41], v[136:137], v[40:41]
	s_nop 0
	v_add_f32_e32 v40, v40, v41
	v_mov_b32_e32 v41, v40
	s_nop 1
	v_permlane16_swap_b32_e32 v41, v40
	s_waitcnt lgkmcnt(0)
	v_add_f32_e32 v40, v40, v41
	v_mov_b32_e32 v41, v40
	s_nop 1
	v_permlane32_swap_b32_e32 v41, v40
	s_waitcnt lgkmcnt(0)
	v_add_f32_e32 v40, v40, v41
	v_fmamk_f32 v134, v40, 0xbc800000, v65
	v_fmamk_f32 v136, v40, 0xbc800000, v63
	v_fmamk_f32 v41, v40, 0xbc800000, v64
	v_fmamk_f32 v135, v40, 0xbc800000, v62
	v_mul_f32_e32 v136, v136, v136
	v_mul_f32_e32 v134, v134, v134
	v_fmac_f32_e32 v136, v135, v135
	v_fmac_f32_e32 v134, v41, v41
	v_fmamk_f32 v135, v40, 0xbc800000, v113
	v_fmamk_f32 v137, v40, 0xbc800000, v111
	v_add_f32_e32 v41, v136, v134
	v_fmamk_f32 v134, v40, 0xbc800000, v112
	v_fmamk_f32 v136, v40, 0xbc800000, v110
	v_mul_f32_e32 v137, v137, v137
	v_mul_f32_e32 v135, v135, v135
	v_fmac_f32_e32 v137, v136, v136
	v_fmac_f32_e32 v135, v134, v134
	v_add_f32_e32 v134, v137, v135
	v_fmamk_f32 v135, v40, 0xbc800000, v53
	v_fmamk_f32 v137, v40, 0xbc800000, v51
	v_add_f32_e32 v41, v41, v134
	v_fmamk_f32 v134, v40, 0xbc800000, v52
	v_fmamk_f32 v136, v40, 0xbc800000, v50
	v_mul_f32_e32 v137, v137, v137
	v_mul_f32_e32 v135, v135, v135
	v_fmac_f32_e32 v137, v136, v136
	v_fmac_f32_e32 v135, v134, v134
	v_add_f32_e32 v134, v137, v135
	v_fmamk_f32 v135, v40, 0xbc800000, v61
	v_fmamk_f32 v137, v40, 0xbc800000, v59
	v_add_f32_e32 v41, v134, v41
	v_fmamk_f32 v134, v40, 0xbc800000, v60
	v_fmamk_f32 v136, v40, 0xbc800000, v58
	v_mul_f32_e32 v137, v137, v137
	v_mul_f32_e32 v135, v135, v135
	v_fmac_f32_e32 v137, v136, v136
	v_fmac_f32_e32 v135, v134, v134
	v_add_f32_e32 v134, v137, v135
	v_add_f32_e32 v41, v134, v41
	v_mov_b32_e32 v134, v41
	s_nop 1
	v_permlane16_swap_b32_e32 v134, v41
	s_waitcnt lgkmcnt(0)
	v_add_f32_e32 v41, v41, v134
	v_mov_b32_e32 v134, v41
	s_nop 1
	v_permlane32_swap_b32_e32 v134, v41
	s_and_saveexec_b64 s[0:1], vcc
	s_cbranch_execz .LBB0_1354
	s_lshl_b32 s4, s9, 11
	s_add_i32 s4, s2, s4
	v_mul_f32_e32 v40, 0x3c800000, v40
	v_lshl_add_u32 v135, v1, 5, s4
	s_waitcnt lgkmcnt(0)
	v_add_f32_e32 v41, v41, v134
	ds_write_b64 v135, v[40:41] offset:4096
.LBB0_1354:
	s_or_b64 exec, exec, s[0:1]
	v_mov_b32_e32 v40, v43
	v_mov_b32_e32 v41, v44
	s_waitcnt lgkmcnt(0)
	v_mov_b32_e32 v134, v42
	v_mov_b32_e32 v135, v45
	v_pk_add_f32 v[40:41], v[40:41], v[134:135]
	v_mov_b32_e32 v134, v55
	v_mov_b32_e32 v135, v56
	v_mov_b32_e32 v136, v54
	v_mov_b32_e32 v137, v57
	v_pk_add_f32 v[134:135], v[134:135], v[136:137]
	v_add_f32_e32 v40, v40, v41
	v_pk_add_f32 v[134:135], v[134:135], v[134:135] op_sel_hi:[0,1]
	v_add_f32_e32 v41, 0, v40
	v_add_f32_e32 v137, v34, v35
	v_add_f32_e32 v139, v36, v37
	v_mov_b32_e32 v136, v46
	v_mov_b32_e32 v138, v47
	v_mov_b32_e32 v134, v48
	v_mov_b32_e32 v40, v49
	v_pk_add_f32 v[136:137], v[136:137], v[138:139]
	v_pk_add_f32 v[40:41], v[134:135], v[40:41]
	s_nop 0
	v_pk_add_f32 v[40:41], v[136:137], v[40:41]
	s_nop 0
	v_add_f32_e32 v40, v40, v41
	v_mov_b32_e32 v41, v40
	s_nop 1
	v_permlane16_swap_b32_e32 v41, v40
	s_waitcnt lgkmcnt(0)
	v_add_f32_e32 v40, v40, v41
	v_mov_b32_e32 v41, v40
	s_nop 1
	v_permlane32_swap_b32_e32 v41, v40
	s_waitcnt lgkmcnt(0)
	v_add_f32_e32 v40, v40, v41
	v_fmamk_f32 v134, v40, 0xbc800000, v45
	v_fmamk_f32 v136, v40, 0xbc800000, v43
	v_fmamk_f32 v41, v40, 0xbc800000, v44
	v_fmamk_f32 v135, v40, 0xbc800000, v42
	v_mul_f32_e32 v136, v136, v136
	v_mul_f32_e32 v134, v134, v134
	v_fmac_f32_e32 v136, v135, v135
	v_fmac_f32_e32 v134, v41, v41
	v_fmamk_f32 v135, v40, 0xbc800000, v57
	v_fmamk_f32 v137, v40, 0xbc800000, v55
	v_add_f32_e32 v41, v136, v134
	v_fmamk_f32 v134, v40, 0xbc800000, v56
	v_fmamk_f32 v136, v40, 0xbc800000, v54
	v_mul_f32_e32 v137, v137, v137
	v_mul_f32_e32 v135, v135, v135
	v_fmac_f32_e32 v137, v136, v136
	v_fmac_f32_e32 v135, v134, v134
	v_add_f32_e32 v134, v137, v135
	v_fmamk_f32 v135, v40, 0xbc800000, v37
	v_fmamk_f32 v137, v40, 0xbc800000, v35
	v_add_f32_e32 v41, v41, v134
	v_fmamk_f32 v134, v40, 0xbc800000, v36
	v_fmamk_f32 v136, v40, 0xbc800000, v34
	v_mul_f32_e32 v137, v137, v137
	v_mul_f32_e32 v135, v135, v135
	v_fmac_f32_e32 v137, v136, v136
	v_fmac_f32_e32 v135, v134, v134
	v_add_f32_e32 v134, v137, v135
	v_fmamk_f32 v135, v40, 0xbc800000, v49
	v_fmamk_f32 v137, v40, 0xbc800000, v47
	v_add_f32_e32 v41, v134, v41
	v_fmamk_f32 v134, v40, 0xbc800000, v48
	v_fmamk_f32 v136, v40, 0xbc800000, v46
	v_mul_f32_e32 v137, v137, v137
	v_mul_f32_e32 v135, v135, v135
	v_fmac_f32_e32 v137, v136, v136
	v_fmac_f32_e32 v135, v134, v134
	v_add_f32_e32 v134, v137, v135
	v_add_f32_e32 v41, v134, v41
	v_mov_b32_e32 v134, v41
	s_nop 1
	v_permlane16_swap_b32_e32 v134, v41
	s_waitcnt lgkmcnt(0)
	v_add_f32_e32 v41, v41, v134
	v_mov_b32_e32 v134, v41
	s_nop 1
	v_permlane32_swap_b32_e32 v134, v41
	s_and_saveexec_b64 s[0:1], vcc
	s_cbranch_execz .LBB0_1356
	s_lshl_b32 s4, s9, 11
	s_add_i32 s4, s2, s4
	v_mul_f32_e32 v40, 0x3c800000, v40
	v_lshl_add_u32 v135, v1, 5, s4
	s_waitcnt lgkmcnt(0)
	v_add_f32_e32 v41, v41, v134
	ds_write_b64 v135, v[40:41] offset:4608
;     __device__ __forceinline__ bool run(const f32x4 (&v)[2][2][4][2], const Unit& u, int wr, int wc, int fr, int fq, PG8_LAS unsigned char* lds, int wid, int lane) const {
;     ...
; #pragma unroll
;         for (int ai = 0; ai < 2; ++ai)
; #pragma unroll
;             for (int m = 0; m < 4; ++m) {
;                 float s = 0.f;
; #pragma unroll
;                 for (int bj = 0; bj < 2; ++bj)
; #pragma unroll
;                     for (int n = 0; n < 2; ++n) { const f32x4 x = v[ai][bj][m][n]; s += (x[0] + x[1]) + (x[2] + x[3]); }
;                 s += __shfl_xor(s, 16); s += __shfl_xor(s, 32);
;                 const float mw = s * (1.0f / 64.0f); float q = 0.f;
; #pragma unroll
;                 for (int bj = 0; bj < 2; ++bj)
; #pragma unroll
;                     for (int n = 0; n < 2; ++n) { const f32x4 d = v[ai][bj][m][n] - mw; q += (d[0] * d[0] + d[1] * d[1]) + (d[2] * d[2] + d[3] * d[3]); }
;                 q += __shfl_xor(q, 16); q += __shfl_xor(q, 32);
;                 if (fq == 0) P[(ai * HALF + wr * 64 + m * 16 + fr) * 4 + wc] = (f32x2v){mw, q};
.LBB0_1356:
	s_or_b64 exec, exec, s[0:1]
	v_mov_b32_e32 v40, v27
	v_mov_b32_e32 v41, v28
	s_waitcnt lgkmcnt(0)
	v_mov_b32_e32 v134, v26
	v_mov_b32_e32 v135, v29
	v_pk_add_f32 v[40:41], v[40:41], v[134:135]
	v_mov_b32_e32 v134, v31
	v_mov_b32_e32 v135, v32
	v_mov_b32_e32 v136, v30
	v_mov_b32_e32 v137, v33
	v_pk_add_f32 v[134:135], v[134:135], v[136:137]
	v_add_f32_e32 v40, v40, v41
	v_pk_add_f32 v[134:135], v[134:135], v[134:135] op_sel_hi:[0,1]
	v_add_f32_e32 v41, 0, v40
	v_add_f32_e32 v137, v22, v23
	v_add_f32_e32 v139, v24, v25
	v_mov_b32_e32 v136, v18
	v_mov_b32_e32 v138, v19
	v_mov_b32_e32 v134, v20
	v_mov_b32_e32 v40, v21
	v_pk_add_f32 v[136:137], v[136:137], v[138:139]
	v_pk_add_f32 v[40:41], v[134:135], v[40:41]
	s_nop 0
	v_pk_add_f32 v[40:41], v[136:137], v[40:41]
	s_nop 0
	v_add_f32_e32 v40, v40, v41
	v_mov_b32_e32 v41, v40
	s_nop 1
	v_permlane16_swap_b32_e32 v41, v40
	s_waitcnt lgkmcnt(0)
	v_add_f32_e32 v40, v40, v41
	v_mov_b32_e32 v41, v40
	s_nop 1
	v_permlane32_swap_b32_e32 v41, v40
	s_waitcnt lgkmcnt(0)
	v_add_f32_e32 v40, v40, v41
	v_fmamk_f32 v134, v40, 0xbc800000, v29
	v_fmamk_f32 v136, v40, 0xbc800000, v27
	v_fmamk_f32 v41, v40, 0xbc800000, v28
	v_fmamk_f32 v135, v40, 0xbc800000, v26
	v_mul_f32_e32 v136, v136, v136
	v_mul_f32_e32 v134, v134, v134
	v_fmac_f32_e32 v136, v135, v135
	v_fmac_f32_e32 v134, v41, v41
	v_fmamk_f32 v135, v40, 0xbc800000, v33
	v_fmamk_f32 v137, v40, 0xbc800000, v31
	v_add_f32_e32 v41, v136, v134
	v_fmamk_f32 v134, v40, 0xbc800000, v32
	v_fmamk_f32 v136, v40, 0xbc800000, v30
	v_mul_f32_e32 v137, v137, v137
	v_mul_f32_e32 v135, v135, v135
	v_fmac_f32_e32 v137, v136, v136
	v_fmac_f32_e32 v135, v134, v134
	v_add_f32_e32 v134, v137, v135
	v_fmamk_f32 v135, v40, 0xbc800000, v25
	v_fmamk_f32 v137, v40, 0xbc800000, v23
	v_add_f32_e32 v41, v41, v134
	v_fmamk_f32 v134, v40, 0xbc800000, v24
	v_fmamk_f32 v136, v40, 0xbc800000, v22
	v_mul_f32_e32 v137, v137, v137
	v_mul_f32_e32 v135, v135, v135
	v_fmac_f32_e32 v137, v136, v136
	v_fmac_f32_e32 v135, v134, v134
	v_add_f32_e32 v134, v137, v135
	v_fmamk_f32 v135, v40, 0xbc800000, v21
	v_fmamk_f32 v137, v40, 0xbc800000, v19
	v_add_f32_e32 v41, v134, v41
	v_fmamk_f32 v134, v40, 0xbc800000, v20
	v_fmamk_f32 v136, v40, 0xbc800000, v18
	v_mul_f32_e32 v137, v137, v137
	v_mul_f32_e32 v135, v135, v135
	v_fmac_f32_e32 v137, v136, v136
	v_fmac_f32_e32 v135, v134, v134
	v_add_f32_e32 v134, v137, v135
	v_add_f32_e32 v41, v134, v41
	v_mov_b32_e32 v134, v41
	s_nop 1
	v_permlane16_swap_b32_e32 v134, v41
	s_waitcnt lgkmcnt(0)
	v_add_f32_e32 v41, v41, v134
	v_mov_b32_e32 v134, v41
	s_nop 1
	v_permlane32_swap_b32_e32 v134, v41
	s_and_saveexec_b64 s[0:1], vcc
	s_cbranch_execz .LBB0_1358
	s_lshl_b32 s4, s9, 11
	s_add_i32 s4, s2, s4
	v_mul_f32_e32 v40, 0x3c800000, v40
	v_lshl_add_u32 v135, v1, 5, s4
	s_waitcnt lgkmcnt(0)
	v_add_f32_e32 v41, v41, v134
	ds_write_b64 v135, v[40:41] offset:5120
.LBB0_1358:
	s_or_b64 exec, exec, s[0:1]
	v_mov_b32_e32 v40, v15
	v_mov_b32_e32 v41, v16
	s_waitcnt lgkmcnt(0)
	v_mov_b32_e32 v134, v14
	v_mov_b32_e32 v135, v17
	v_pk_add_f32 v[40:41], v[40:41], v[134:135]
	v_mov_b32_e32 v134, v11
	v_mov_b32_e32 v135, v12
	v_mov_b32_e32 v136, v10
	v_mov_b32_e32 v137, v13
	v_pk_add_f32 v[134:135], v[134:135], v[136:137]
	v_add_f32_e32 v40, v40, v41
	v_pk_add_f32 v[134:135], v[134:135], v[134:135] op_sel_hi:[0,1]
	v_add_f32_e32 v41, 0, v40
	v_add_f32_e32 v137, v6, v7
	v_add_f32_e32 v139, v8, v9
	v_mov_b32_e32 v136, v2
	v_mov_b32_e32 v138, v3
	v_mov_b32_e32 v134, v4
	v_mov_b32_e32 v40, v5
	v_pk_add_f32 v[136:137], v[136:137], v[138:139]
	v_pk_add_f32 v[40:41], v[134:135], v[40:41]
	s_nop 0
	v_pk_add_f32 v[40:41], v[136:137], v[40:41]
	s_nop 0
	v_add_f32_e32 v40, v40, v41
	v_mov_b32_e32 v41, v40
	s_nop 1
	v_permlane16_swap_b32_e32 v41, v40
	s_waitcnt lgkmcnt(0)
	v_add_f32_e32 v40, v40, v41
	v_mov_b32_e32 v41, v40
	s_nop 1
	v_permlane32_swap_b32_e32 v41, v40
	s_waitcnt lgkmcnt(0)
	v_add_f32_e32 v40, v40, v41
	v_fmamk_f32 v134, v40, 0xbc800000, v17
	v_fmamk_f32 v136, v40, 0xbc800000, v15
	v_fmamk_f32 v41, v40, 0xbc800000, v16
	v_fmamk_f32 v135, v40, 0xbc800000, v14
	v_mul_f32_e32 v136, v136, v136
	v_mul_f32_e32 v134, v134, v134
	v_fmac_f32_e32 v136, v135, v135
	v_fmac_f32_e32 v134, v41, v41
	v_fmamk_f32 v135, v40, 0xbc800000, v13
	v_fmamk_f32 v137, v40, 0xbc800000, v11
	v_add_f32_e32 v41, v136, v134
	v_fmamk_f32 v134, v40, 0xbc800000, v12
	v_fmamk_f32 v136, v40, 0xbc800000, v10
	v_mul_f32_e32 v137, v137, v137
	v_mul_f32_e32 v135, v135, v135
	v_fmac_f32_e32 v137, v136, v136
	v_fmac_f32_e32 v135, v134, v134
	v_add_f32_e32 v134, v137, v135
	v_fmamk_f32 v135, v40, 0xbc800000, v9
	v_fmamk_f32 v137, v40, 0xbc800000, v7
	v_add_f32_e32 v41, v41, v134
	v_fmamk_f32 v134, v40, 0xbc800000, v8
	v_fmamk_f32 v136, v40, 0xbc800000, v6
	v_mul_f32_e32 v137, v137, v137
	v_mul_f32_e32 v135, v135, v135
	v_fmac_f32_e32 v137, v136, v136
	v_fmac_f32_e32 v135, v134, v134
	v_add_f32_e32 v134, v137, v135
	v_fmamk_f32 v135, v40, 0xbc800000, v5
	v_fmamk_f32 v137, v40, 0xbc800000, v3
	v_add_f32_e32 v41, v134, v41
	v_fmamk_f32 v134, v40, 0xbc800000, v4
	v_fmamk_f32 v136, v40, 0xbc800000, v2
	v_mul_f32_e32 v137, v137, v137
	v_mul_f32_e32 v135, v135, v135
	v_fmac_f32_e32 v137, v136, v136
	v_fmac_f32_e32 v135, v134, v134
	v_add_f32_e32 v134, v137, v135
	v_add_f32_e32 v41, v134, v41
	v_mov_b32_e32 v38, v41
	s_nop 1
	v_permlane16_swap_b32_e32 v38, v41
	s_waitcnt lgkmcnt(0)
	v_add_f32_e32 v38, v41, v38
	v_mov_b32_e32 v39, v38
	s_nop 1
	v_permlane32_swap_b32_e32 v39, v38
	s_and_saveexec_b64 s[0:1], vcc
	s_cbranch_execz .LBB0_1360
	s_lshl_b32 s4, s9, 11
	s_add_i32 s2, s2, s4
	v_mul_f32_e32 v40, 0x3c800000, v40
	v_lshl_add_u32 v1, v1, 5, s2
	s_waitcnt lgkmcnt(0)
	v_add_f32_e32 v41, v38, v39
	ds_write_b64 v1, v[40:41] offset:5632
